# GEMM loops: k-inner MFMA pairs with k order alternating so consecutive pairs share one operand (accumulation order k1,k0 for half the accumulators)
# baseline (speedup 1.0000x reference)
; #define PG8_STAGE(bufoff, gbase, voff) do { _Pragma("unroll") for (int _i = 0; _i < 2; ++_i) \
;         __builtin_amdgcn_global_load_lds((const unsigned*)((const char*)(gbase) + (voff)[_i]), (LAS unsigned*)(lds + (bufoff) + ldsw + _i * 8192), 16, 0, 0); } while (0)
; #define PG8_LDA(dst, b, h) do { _Pragma("unroll") for (int m = 0; m < 4; ++m) _Pragma("unroll") for (int k = 0; k < 2; ++k) dst[m][k] = *(const LAS bf16x8*)(lds + PG8_SA(b, h) + aoff + m * 2048 + k * 1024); } while (0)
; #define PG8_LDB(dst, b, h) do { _Pragma("unroll") for (int n = 0; n < 2; ++n) _Pragma("unroll") for (int k = 0; k < 2; ++k) dst[n][k] = *(const LAS bf16x8*)(lds + PG8_SB(b, h) + boff + n * 2048 + k * 1024); } while (0)
; #define PG8_WAIT_V(n) asm volatile("s_waitcnt vmcnt(" #n ")" ::: "memory")
; #define PG8_WAIT_L(n) asm volatile("s_waitcnt lgkmcnt(" #n ")" ::: "memory")
; #define PG8_BAR __builtin_amdgcn_s_barrier()
; #define PG8_SCHED __builtin_amdgcn_sched_barrier(0)
; template <class Epi, class Sched, bool ALIGN_EPI = false, bool SP2 = false>
; __device__ __forceinline__ void gemm_phase(LAS unsigned char* lds, const Gemm g, const Sched& S, const Epi& E) {
;     ...
;         const bool has_next = S.next(ui + 1, nxt);
;         const char* nA = has_next ? (const char*)g.A + (size_t)nxt.pm * tstep : cA; const char* nB = has_next ? (const char*)g.Bt + (size_t)nxt.pn * tstep : cB;
;         for (int t = 0; t < nt; t += 2) {
;             const bool last = (t == nt - 2);
;             const char* a1 = cA + (size_t)(t + 1) * kstep;
;             const char* a2 = last ? nA : cA + (size_t)(t + 2) * kstep; const char* b2 = last ? nB : cB + (size_t)(t + 2) * kstep;
;             const char* a3 = a2 + kstep; const char* b3 = b2 + kstep;
;             if (last && has_next) S.a_ready(nxt);
;             if constexpr (SP2) {
;             PG8_LDB(B0, 0, 0); PG8_LDB(B1, 0, 1); PG8_SCHED; PG8_LDA(At, 0, 0); PG8_STAGE(PG8_SA(1, 1), a1 + hstep, voffA);
;             PG8_WAIT_V(8); PG8_WAIT_L(0); PG8_BAR; PG8_MMA(0, 0, At, B0); PG8_MMA(0, 1, At, B1); PG8_BAR; PG8_SCHED;
;             PG8_LDA(At, 0, 1); PG8_STAGE(PG8_SB(0, 0), b2, voffB); PG8_STAGE(PG8_SB(0, 1), b2 + hstep, voffB); PG8_STAGE(PG8_SA(0, 0), a2, voffA);
;             PG8_WAIT_V(8); PG8_WAIT_L(0); PG8_BAR; PG8_MMA(1, 0, At, B0); PG8_MMA(1, 1, At, B1); PG8_BAR; PG8_SCHED;
.LBB0_173:
	s_add_u32 s26, s24, 0xfff80080
	s_addc_u32 s27, s25, -1
	s_add_i32 s45, 0, 0x10000
	s_cmp_eq_u32 s44, 28
	s_cselect_b32 s29, s7, s27
	s_cselect_b32 s28, s8, s26
	v_add_u32_e32 v140, s45, v145
	s_cselect_b32 s27, s17, s43
	s_cselect_b32 s26, s19, s35
	s_add_i32 s47, 0, 0x14000
	ds_read_b128 v[150:153], v140
	ds_read_b128 v[154:157], v140 offset:1024
	ds_read_b128 v[158:161], v140 offset:2048
	ds_read_b128 v[162:165], v140 offset:3072
	v_add_u32_e32 v140, s47, v145
	ds_read_b128 v[166:169], v140
	ds_read_b128 v[170:173], v140 offset:1024
	ds_read_b128 v[174:177], v140 offset:2048
	ds_read_b128 v[178:181], v140 offset:3072
	v_lshl_add_u64 v[140:141], s[24:25], 0, v[136:137]
	s_add_i32 m0, s30, 0xc000
	ds_read_b128 v[182:185], v149
	ds_read_b128 v[194:197], v149 offset:1024
	ds_read_b128 v[198:201], v149 offset:2048
	ds_read_b128 v[202:205], v149 offset:3072
	ds_read_b128 v[206:209], v149 offset:4096
	ds_read_b128 v[210:213], v149 offset:5120
	ds_read_b128 v[214:217], v149 offset:6144
	ds_read_b128 v[218:221], v149 offset:7168
	global_load_lds_dwordx4 v[140:141], off
	v_lshl_add_u64 v[140:141], s[24:25], 0, v[138:139]
	s_add_i32 m0, s30, 0xe000
	s_nop 0
	global_load_lds_dwordx4 v[140:141], off
	s_waitcnt vmcnt(8)
	s_waitcnt lgkmcnt(0)
	s_barrier
	s_setprio 1
	s_waitcnt lgkmcnt(0)
	v_mfma_f32_16x16x32_bf16 v[126:129], v[150:153], v[182:185], v[126:129]
	v_mfma_f32_16x16x32_bf16 v[126:129], v[154:157], v[194:197], v[126:129]
	v_mfma_f32_16x16x32_bf16 v[122:125], v[162:165], v[194:197], v[122:125]
	v_mfma_f32_16x16x32_bf16 v[122:125], v[158:161], v[182:185], v[122:125]
	v_mfma_f32_16x16x32_bf16 v[106:109], v[158:161], v[198:201], v[106:109]
	v_mfma_f32_16x16x32_bf16 v[106:109], v[162:165], v[202:205], v[106:109]
	v_mfma_f32_16x16x32_bf16 v[110:113], v[154:157], v[202:205], v[110:113]
	v_mfma_f32_16x16x32_bf16 v[110:113], v[150:153], v[198:201], v[110:113]
	v_mfma_f32_16x16x32_bf16 v[94:97], v[150:153], v[206:209], v[94:97]
	v_mfma_f32_16x16x32_bf16 v[94:97], v[154:157], v[210:213], v[94:97]
	v_mfma_f32_16x16x32_bf16 v[90:93], v[162:165], v[210:213], v[90:93]
	v_mfma_f32_16x16x32_bf16 v[90:93], v[158:161], v[206:209], v[90:93]
	v_mfma_f32_16x16x32_bf16 v[74:77], v[158:161], v[214:217], v[74:77]
	v_mfma_f32_16x16x32_bf16 v[74:77], v[162:165], v[218:221], v[74:77]
	v_mfma_f32_16x16x32_bf16 v[78:81], v[154:157], v[218:221], v[78:81]
	v_mfma_f32_16x16x32_bf16 v[78:81], v[150:153], v[214:217], v[78:81]
	s_setprio 0
	s_setprio 1
	v_mfma_f32_16x16x32_bf16 v[118:121], v[166:169], v[182:185], v[118:121]
	v_mfma_f32_16x16x32_bf16 v[118:121], v[170:173], v[194:197], v[118:121]
	v_mfma_f32_16x16x32_bf16 v[114:117], v[178:181], v[194:197], v[114:117]
	v_mfma_f32_16x16x32_bf16 v[114:117], v[174:177], v[182:185], v[114:117]
	v_mfma_f32_16x16x32_bf16 v[98:101], v[174:177], v[198:201], v[98:101]
	v_mfma_f32_16x16x32_bf16 v[98:101], v[178:181], v[202:205], v[98:101]
	v_mfma_f32_16x16x32_bf16 v[102:105], v[170:173], v[202:205], v[102:105]
	v_mfma_f32_16x16x32_bf16 v[102:105], v[166:169], v[198:201], v[102:105]
	v_mfma_f32_16x16x32_bf16 v[86:89], v[166:169], v[206:209], v[86:89]
	v_mfma_f32_16x16x32_bf16 v[86:89], v[170:173], v[210:213], v[86:89]
	v_mfma_f32_16x16x32_bf16 v[82:85], v[178:181], v[210:213], v[82:85]
	v_mfma_f32_16x16x32_bf16 v[82:85], v[174:177], v[206:209], v[82:85]
	v_mfma_f32_16x16x32_bf16 v[66:69], v[174:177], v[214:217], v[66:69]
	v_mfma_f32_16x16x32_bf16 v[66:69], v[178:181], v[218:221], v[66:69]
	v_mfma_f32_16x16x32_bf16 v[70:73], v[170:173], v[218:221], v[70:73]
	v_mfma_f32_16x16x32_bf16 v[70:73], v[166:169], v[214:217], v[70:73]
	s_setprio 0
	s_barrier
	s_add_i32 s45, s45, s9
	v_lshl_add_u64 v[140:141], s[26:27], 0, v[0:1]
	s_mov_b32 m0, s45
	ds_read_b128 v[182:185], v149 offset:16384
	ds_read_b128 v[194:197], v149 offset:17408
	ds_read_b128 v[198:201], v149 offset:18432
	ds_read_b128 v[202:205], v149 offset:19456
	ds_read_b128 v[206:209], v149 offset:20480
	ds_read_b128 v[210:213], v149 offset:21504
	ds_read_b128 v[214:217], v149 offset:22528
	ds_read_b128 v[218:221], v149 offset:23552
	global_load_lds_dwordx4 v[140:141], off
	s_add_i32 m0, s45, 0x2000
	s_add_u32 s48, s26, 0x80000
	v_lshl_add_u64 v[186:187], s[26:27], 0, v[130:131]
	s_addc_u32 s49, s27, 0
	s_add_i32 s45, s47, s9
	global_load_lds_dwordx4 v[186:187], off
	v_lshl_add_u64 v[188:189], s[48:49], 0, v[0:1]
	s_mov_b32 m0, s45
	v_lshl_add_u64 v[190:191], s[28:29], 0, v[132:133]
	global_load_lds_dwordx4 v[188:189], off
	v_lshl_add_u64 v[188:189], s[48:49], 0, v[130:131]
	s_add_i32 m0, s45, 0x2000
	s_nop 0
	global_load_lds_dwordx4 v[188:189], off
	v_lshl_add_u64 v[188:189], s[28:29], 0, v[134:135]
	s_mov_b32 m0, s30
	s_nop 0
	global_load_lds_dwordx4 v[188:189], off
	s_mov_b32 m0, s31
	s_nop 0
	global_load_lds_dwordx4 v[190:191], off
	s_waitcnt vmcnt(8)
	s_waitcnt lgkmcnt(0)
	s_barrier
; #define PG8_STAGE(bufoff, gbase, voff) do { _Pragma("unroll") for (int _i = 0; _i < 2; ++_i) \
;         __builtin_amdgcn_global_load_lds((const unsigned*)((const char*)(gbase) + (voff)[_i]), (LAS unsigned*)(lds + (bufoff) + ldsw + _i * 8192), 16, 0, 0); } while (0)
; #define PG8_LDA(dst, b, h) do { _Pragma("unroll") for (int m = 0; m < 4; ++m) _Pragma("unroll") for (int k = 0; k < 2; ++k) dst[m][k] = *(const LAS bf16x8*)(lds + PG8_SA(b, h) + aoff + m * 2048 + k * 1024); } while (0)
; #define PG8_LDB(dst, b, h) do { _Pragma("unroll") for (int n = 0; n < 2; ++n) _Pragma("unroll") for (int k = 0; k < 2; ++k) dst[n][k] = *(const LAS bf16x8*)(lds + PG8_SB(b, h) + boff + n * 2048 + k * 1024); } while (0)
; #define PG8_MMA(ai, bj, At, Bt) do { __builtin_amdgcn_s_setprio(1); _Pragma("unroll") for (int m = 0; m < 4; ++m) _Pragma("unroll") for (int n = 0; n < 2; ++n) _Pragma("unroll") for (int k = 0; k < 2; ++k) \
;         acc[ai][bj][m][n] = __builtin_amdgcn_mfma_f32_16x16x32_bf16(Bt[n][k], At[m][k], acc[ai][bj][m][n], 0, 0, 0); __builtin_amdgcn_s_setprio(0); } while (0)
; #define PG8_WAIT_V(n) asm volatile("s_waitcnt vmcnt(" #n ")" ::: "memory")
; #define PG8_WAIT_L(n) asm volatile("s_waitcnt lgkmcnt(" #n ")" ::: "memory")
; #define PG8_BAR __builtin_amdgcn_s_barrier()
; #define PG8_SCHED __builtin_amdgcn_sched_barrier(0)
; template <class Epi, class Sched, bool ALIGN_EPI = false, bool SP2 = false>
; __device__ __forceinline__ void gemm_phase(LAS unsigned char* lds, const Gemm g, const Sched& S, const Epi& E) {
;     ...
;             PG8_WAIT_V(8); PG8_WAIT_L(0); PG8_BAR; PG8_MMA(1, 0, At, B0); PG8_MMA(1, 1, At, B1); PG8_BAR; PG8_SCHED;
;             PG8_LDB(B0, 1, 0); PG8_LDB(B1, 1, 1); PG8_SCHED; PG8_LDA(At, 1, 0); PG8_STAGE(PG8_SA(0, 1), a2 + hstep, voffA);
;             PG8_WAIT_V(8); PG8_WAIT_L(0); PG8_BAR; PG8_MMA(0, 0, At, B0); PG8_MMA(0, 1, At, B1); PG8_BAR; PG8_SCHED;
	s_setprio 1
	s_waitcnt lgkmcnt(0)
	v_mfma_f32_16x16x32_bf16 v[62:65], v[150:153], v[182:185], v[62:65]
	v_mfma_f32_16x16x32_bf16 v[62:65], v[154:157], v[194:197], v[62:65]
	v_mfma_f32_16x16x32_bf16 v[58:61], v[162:165], v[194:197], v[58:61]
	v_mfma_f32_16x16x32_bf16 v[58:61], v[158:161], v[182:185], v[58:61]
	v_mfma_f32_16x16x32_bf16 v[42:45], v[158:161], v[198:201], v[42:45]
	v_mfma_f32_16x16x32_bf16 v[42:45], v[162:165], v[202:205], v[42:45]
	v_mfma_f32_16x16x32_bf16 v[46:49], v[154:157], v[202:205], v[46:49]
	v_mfma_f32_16x16x32_bf16 v[46:49], v[150:153], v[198:201], v[46:49]
	v_mfma_f32_16x16x32_bf16 v[30:33], v[150:153], v[206:209], v[30:33]
	v_mfma_f32_16x16x32_bf16 v[30:33], v[154:157], v[210:213], v[30:33]
	v_mfma_f32_16x16x32_bf16 v[26:29], v[162:165], v[210:213], v[26:29]
	v_mfma_f32_16x16x32_bf16 v[26:29], v[158:161], v[206:209], v[26:29]
	v_mfma_f32_16x16x32_bf16 v[10:13], v[158:161], v[214:217], v[10:13]
	v_mfma_f32_16x16x32_bf16 v[10:13], v[162:165], v[218:221], v[10:13]
	v_mfma_f32_16x16x32_bf16 v[14:17], v[154:157], v[218:221], v[14:17]
	v_mfma_f32_16x16x32_bf16 v[14:17], v[150:153], v[214:217], v[14:17]
	s_setprio 0
	s_setprio 1
	v_mfma_f32_16x16x32_bf16 v[54:57], v[166:169], v[182:185], v[54:57]
	v_mfma_f32_16x16x32_bf16 v[54:57], v[170:173], v[194:197], v[54:57]
	v_mfma_f32_16x16x32_bf16 v[50:53], v[178:181], v[194:197], v[50:53]
	v_mfma_f32_16x16x32_bf16 v[50:53], v[174:177], v[182:185], v[50:53]
	v_mfma_f32_16x16x32_bf16 v[34:37], v[174:177], v[198:201], v[34:37]
	v_mfma_f32_16x16x32_bf16 v[34:37], v[178:181], v[202:205], v[34:37]
	v_mfma_f32_16x16x32_bf16 v[38:41], v[170:173], v[202:205], v[38:41]
	v_mfma_f32_16x16x32_bf16 v[38:41], v[166:169], v[198:201], v[38:41]
	v_mfma_f32_16x16x32_bf16 v[22:25], v[166:169], v[206:209], v[22:25]
	v_mfma_f32_16x16x32_bf16 v[22:25], v[170:173], v[210:213], v[22:25]
	v_mfma_f32_16x16x32_bf16 v[18:21], v[178:181], v[210:213], v[18:21]
	v_mfma_f32_16x16x32_bf16 v[18:21], v[174:177], v[206:209], v[18:21]
	v_mfma_f32_16x16x32_bf16 v[2:5], v[174:177], v[214:217], v[2:5]
	v_mfma_f32_16x16x32_bf16 v[2:5], v[178:181], v[218:221], v[2:5]
	v_mfma_f32_16x16x32_bf16 v[6:9], v[170:173], v[218:221], v[6:9]
	v_mfma_f32_16x16x32_bf16 v[6:9], v[166:169], v[214:217], v[6:9]
	s_setprio 0
	s_barrier
	s_add_i32 s45, 0, 0x18000
	v_add_u32_e32 v142, s45, v145
	s_add_i32 s47, 0, 0x1c000
	ds_read_b128 v[150:153], v142
	ds_read_b128 v[154:157], v142 offset:1024
	ds_read_b128 v[158:161], v142 offset:2048
	ds_read_b128 v[162:165], v142 offset:3072
	v_add_u32_e32 v142, s47, v145
	ds_read_b128 v[166:169], v142
	ds_read_b128 v[170:173], v142 offset:1024
	ds_read_b128 v[174:177], v142 offset:2048
	ds_read_b128 v[178:181], v142 offset:3072
	s_add_u32 s28, s28, 0x80000
	s_addc_u32 s29, s29, 0
	s_mov_b32 m0, s38
	v_lshl_add_u64 v[192:193], s[28:29], 0, v[134:135]
	ds_read_b128 v[182:185], v149 offset:32768
	ds_read_b128 v[194:197], v149 offset:33792
	ds_read_b128 v[198:201], v149 offset:34816
	ds_read_b128 v[202:205], v149 offset:35840
	ds_read_b128 v[206:209], v149 offset:36864
	ds_read_b128 v[210:213], v149 offset:37888
	ds_read_b128 v[214:217], v149 offset:38912
	ds_read_b128 v[218:221], v149 offset:39936
	global_load_lds_dwordx4 v[192:193], off
	v_lshl_add_u64 v[192:193], s[28:29], 0, v[132:133]
	s_mov_b32 m0, s39
	s_nop 0
	global_load_lds_dwordx4 v[192:193], off
	s_waitcnt vmcnt(8)
	s_waitcnt lgkmcnt(0)
	s_barrier
	s_setprio 1
	s_waitcnt lgkmcnt(0)
	v_mfma_f32_16x16x32_bf16 v[126:129], v[150:153], v[182:185], v[126:129]
	v_mfma_f32_16x16x32_bf16 v[126:129], v[154:157], v[194:197], v[126:129]
	v_mfma_f32_16x16x32_bf16 v[122:125], v[162:165], v[194:197], v[122:125]
	v_mfma_f32_16x16x32_bf16 v[122:125], v[158:161], v[182:185], v[122:125]
	v_mfma_f32_16x16x32_bf16 v[106:109], v[158:161], v[198:201], v[106:109]
	v_mfma_f32_16x16x32_bf16 v[106:109], v[162:165], v[202:205], v[106:109]
	v_mfma_f32_16x16x32_bf16 v[110:113], v[154:157], v[202:205], v[110:113]
	v_mfma_f32_16x16x32_bf16 v[110:113], v[150:153], v[198:201], v[110:113]
	v_mfma_f32_16x16x32_bf16 v[94:97], v[150:153], v[206:209], v[94:97]
	v_mfma_f32_16x16x32_bf16 v[94:97], v[154:157], v[210:213], v[94:97]
	v_mfma_f32_16x16x32_bf16 v[90:93], v[162:165], v[210:213], v[90:93]
	v_mfma_f32_16x16x32_bf16 v[90:93], v[158:161], v[206:209], v[90:93]
	v_mfma_f32_16x16x32_bf16 v[74:77], v[158:161], v[214:217], v[74:77]
	v_mfma_f32_16x16x32_bf16 v[74:77], v[162:165], v[218:221], v[74:77]
	v_mfma_f32_16x16x32_bf16 v[78:81], v[154:157], v[218:221], v[78:81]
	v_mfma_f32_16x16x32_bf16 v[78:81], v[150:153], v[214:217], v[78:81]
	s_setprio 0
	s_setprio 1
	v_mfma_f32_16x16x32_bf16 v[118:121], v[166:169], v[182:185], v[118:121]
	v_mfma_f32_16x16x32_bf16 v[118:121], v[170:173], v[194:197], v[118:121]
	v_mfma_f32_16x16x32_bf16 v[114:117], v[178:181], v[194:197], v[114:117]
	v_mfma_f32_16x16x32_bf16 v[114:117], v[174:177], v[182:185], v[114:117]
	v_mfma_f32_16x16x32_bf16 v[98:101], v[174:177], v[198:201], v[98:101]
	v_mfma_f32_16x16x32_bf16 v[98:101], v[178:181], v[202:205], v[98:101]
	v_mfma_f32_16x16x32_bf16 v[102:105], v[170:173], v[202:205], v[102:105]
	v_mfma_f32_16x16x32_bf16 v[102:105], v[166:169], v[198:201], v[102:105]
	v_mfma_f32_16x16x32_bf16 v[86:89], v[166:169], v[206:209], v[86:89]
	v_mfma_f32_16x16x32_bf16 v[86:89], v[170:173], v[210:213], v[86:89]
	v_mfma_f32_16x16x32_bf16 v[82:85], v[178:181], v[210:213], v[82:85]
	v_mfma_f32_16x16x32_bf16 v[82:85], v[174:177], v[206:209], v[82:85]
	v_mfma_f32_16x16x32_bf16 v[66:69], v[174:177], v[214:217], v[66:69]
	v_mfma_f32_16x16x32_bf16 v[66:69], v[178:181], v[218:221], v[66:69]
	v_mfma_f32_16x16x32_bf16 v[70:73], v[170:173], v[218:221], v[70:73]
	v_mfma_f32_16x16x32_bf16 v[70:73], v[166:169], v[214:217], v[70:73]
	s_setprio 0
	s_barrier
; #define PG8_STAGE(bufoff, gbase, voff) do { _Pragma("unroll") for (int _i = 0; _i < 2; ++_i) \
;         __builtin_amdgcn_global_load_lds((const unsigned*)((const char*)(gbase) + (voff)[_i]), (LAS unsigned*)(lds + (bufoff) + ldsw + _i * 8192), 16, 0, 0); } while (0)
; #define PG8_LDA(dst, b, h) do { _Pragma("unroll") for (int m = 0; m < 4; ++m) _Pragma("unroll") for (int k = 0; k < 2; ++k) dst[m][k] = *(const LAS bf16x8*)(lds + PG8_SA(b, h) + aoff + m * 2048 + k * 1024); } while (0)
; #define PG8_MMA(ai, bj, At, Bt) do { __builtin_amdgcn_s_setprio(1); _Pragma("unroll") for (int m = 0; m < 4; ++m) _Pragma("unroll") for (int n = 0; n < 2; ++n) _Pragma("unroll") for (int k = 0; k < 2; ++k) \
;         acc[ai][bj][m][n] = __builtin_amdgcn_mfma_f32_16x16x32_bf16(Bt[n][k], At[m][k], acc[ai][bj][m][n], 0, 0, 0); __builtin_amdgcn_s_setprio(0); } while (0)
; #define PG8_WAIT_V(n) asm volatile("s_waitcnt vmcnt(" #n ")" ::: "memory")
; #define PG8_WAIT_L(n) asm volatile("s_waitcnt lgkmcnt(" #n ")" ::: "memory")
; #define PG8_BAR __builtin_amdgcn_s_barrier()
; #define PG8_SCHED __builtin_amdgcn_sched_barrier(0)
; template <class Epi, class Sched, bool ALIGN_EPI = false, bool SP2 = false>
; __device__ __forceinline__ void gemm_phase(LAS unsigned char* lds, const Gemm g, const Sched& S, const Epi& E) {
;     ...
;             PG8_LDA(At, 1, 1); PG8_STAGE(PG8_SB(1, 0), b3, voffB); PG8_STAGE(PG8_SB(1, 1), b3 + hstep, voffB); PG8_STAGE(PG8_SA(1, 0), a3, voffA);
;             PG8_WAIT_V(8); PG8_WAIT_L(0); PG8_BAR; PG8_MMA(1, 0, At, B0); PG8_MMA(1, 1, At, B1); PG8_BAR; PG8_SCHED;
	s_add_i32 s28, s45, s9
	v_lshl_add_u64 v[140:141], v[140:141], 0, s[12:13]
	s_mov_b32 m0, s28
	ds_read_b128 v[182:185], v149 offset:49152
	ds_read_b128 v[194:197], v149 offset:50176
	ds_read_b128 v[198:201], v149 offset:51200
	ds_read_b128 v[202:205], v149 offset:52224
	ds_read_b128 v[206:209], v149 offset:53248
	ds_read_b128 v[210:213], v149 offset:54272
	ds_read_b128 v[214:217], v149 offset:55296
	ds_read_b128 v[218:221], v149 offset:56320
	global_load_lds_dwordx4 v[140:141], off
	s_add_i32 m0, s28, 0x2000
	s_add_u32 s26, s26, 0x80080
	v_lshl_add_u64 v[140:141], v[186:187], 0, s[12:13]
	s_addc_u32 s27, s27, 0
	s_add_i32 s28, s47, s9
	global_load_lds_dwordx4 v[140:141], off
	v_lshl_add_u64 v[140:141], s[26:27], 0, v[0:1]
	s_mov_b32 m0, s28
	s_nop 0
	global_load_lds_dwordx4 v[140:141], off
	v_lshl_add_u64 v[140:141], s[26:27], 0, v[130:131]
	s_add_i32 m0, s28, 0x2000
	s_nop 0
	global_load_lds_dwordx4 v[140:141], off
	v_lshl_add_u64 v[140:141], v[188:189], 0, s[12:13]
	s_mov_b32 m0, s40
	s_nop 0
	global_load_lds_dwordx4 v[140:141], off
	v_lshl_add_u64 v[140:141], v[190:191], 0, s[12:13]
	s_mov_b32 m0, s41
	s_nop 0
	global_load_lds_dwordx4 v[140:141], off
	s_waitcnt vmcnt(8)
	s_waitcnt lgkmcnt(0)
	s_barrier
	s_setprio 1
	s_waitcnt lgkmcnt(0)
	v_mfma_f32_16x16x32_bf16 v[62:65], v[150:153], v[182:185], v[62:65]
	v_mfma_f32_16x16x32_bf16 v[62:65], v[154:157], v[194:197], v[62:65]
	v_mfma_f32_16x16x32_bf16 v[58:61], v[162:165], v[194:197], v[58:61]
	v_mfma_f32_16x16x32_bf16 v[58:61], v[158:161], v[182:185], v[58:61]
	v_mfma_f32_16x16x32_bf16 v[42:45], v[158:161], v[198:201], v[42:45]
	v_mfma_f32_16x16x32_bf16 v[42:45], v[162:165], v[202:205], v[42:45]
	v_mfma_f32_16x16x32_bf16 v[46:49], v[154:157], v[202:205], v[46:49]
	v_mfma_f32_16x16x32_bf16 v[46:49], v[150:153], v[198:201], v[46:49]
	v_mfma_f32_16x16x32_bf16 v[30:33], v[150:153], v[206:209], v[30:33]
	v_mfma_f32_16x16x32_bf16 v[30:33], v[154:157], v[210:213], v[30:33]
	v_mfma_f32_16x16x32_bf16 v[26:29], v[162:165], v[210:213], v[26:29]
	v_mfma_f32_16x16x32_bf16 v[26:29], v[158:161], v[206:209], v[26:29]
	v_mfma_f32_16x16x32_bf16 v[10:13], v[158:161], v[214:217], v[10:13]
	v_mfma_f32_16x16x32_bf16 v[10:13], v[162:165], v[218:221], v[10:13]
	v_mfma_f32_16x16x32_bf16 v[14:17], v[154:157], v[218:221], v[14:17]
	v_mfma_f32_16x16x32_bf16 v[14:17], v[150:153], v[214:217], v[14:17]
	s_setprio 0
	s_setprio 1
	v_mfma_f32_16x16x32_bf16 v[54:57], v[166:169], v[182:185], v[54:57]
	v_mfma_f32_16x16x32_bf16 v[54:57], v[170:173], v[194:197], v[54:57]
	v_mfma_f32_16x16x32_bf16 v[50:53], v[178:181], v[194:197], v[50:53]
	v_mfma_f32_16x16x32_bf16 v[50:53], v[174:177], v[182:185], v[50:53]
	v_mfma_f32_16x16x32_bf16 v[34:37], v[174:177], v[198:201], v[34:37]
	v_mfma_f32_16x16x32_bf16 v[34:37], v[178:181], v[202:205], v[34:37]
	v_mfma_f32_16x16x32_bf16 v[38:41], v[170:173], v[202:205], v[38:41]
	v_mfma_f32_16x16x32_bf16 v[38:41], v[166:169], v[198:201], v[38:41]
	v_mfma_f32_16x16x32_bf16 v[22:25], v[166:169], v[206:209], v[22:25]
	v_mfma_f32_16x16x32_bf16 v[22:25], v[170:173], v[210:213], v[22:25]
	v_mfma_f32_16x16x32_bf16 v[18:21], v[178:181], v[210:213], v[18:21]
	v_mfma_f32_16x16x32_bf16 v[18:21], v[174:177], v[206:209], v[18:21]
	v_mfma_f32_16x16x32_bf16 v[2:5], v[174:177], v[214:217], v[2:5]
	v_mfma_f32_16x16x32_bf16 v[2:5], v[178:181], v[218:221], v[2:5]
	v_mfma_f32_16x16x32_bf16 v[6:9], v[170:173], v[218:221], v[6:9]
	v_mfma_f32_16x16x32_bf16 v[6:9], v[166:169], v[214:217], v[6:9]
	s_setprio 0
	s_barrier
	s_add_i32 s44, s44, 2
	s_add_u32 s24, s24, 0x100
	s_addc_u32 s25, s25, 0
	s_add_u32 s35, s35, 0x100
	s_addc_u32 s43, s43, 0
	s_cmp_gt_u32 s44, 29
	s_cbranch_scc0 .LBB0_173
	s_and_b64 vcc, exec, s[4:5]
	s_cbranch_vccz .LBB0_176
	s_barrier

; #define PG8_STAGE(bufoff, gbase, voff) do { _Pragma("unroll") for (int _i = 0; _i < 2; ++_i) \
;         __builtin_amdgcn_global_load_lds((const unsigned*)((const char*)(gbase) + (voff)[_i]), (LAS unsigned*)(lds + (bufoff) + ldsw + _i * 8192), 16, 0, 0); } while (0)
; #define PG8_LDA(dst, b, h) do { _Pragma("unroll") for (int m = 0; m < 4; ++m) _Pragma("unroll") for (int k = 0; k < 2; ++k) dst[m][k] = *(const LAS bf16x8*)(lds + PG8_SA(b, h) + aoff + m * 2048 + k * 1024); } while (0)
; #define PG8_LDB(dst, b, h) do { _Pragma("unroll") for (int n = 0; n < 2; ++n) _Pragma("unroll") for (int k = 0; k < 2; ++k) dst[n][k] = *(const LAS bf16x8*)(lds + PG8_SB(b, h) + boff + n * 2048 + k * 1024); } while (0)
; #define PG8_MMA(ai, bj, At, Bt) do { __builtin_amdgcn_s_setprio(1); _Pragma("unroll") for (int m = 0; m < 4; ++m) _Pragma("unroll") for (int n = 0; n < 2; ++n) _Pragma("unroll") for (int k = 0; k < 2; ++k) \
;         acc[ai][bj][m][n] = __builtin_amdgcn_mfma_f32_16x16x32_bf16(Bt[n][k], At[m][k], acc[ai][bj][m][n], 0, 0, 0); __builtin_amdgcn_s_setprio(0); } while (0)
; #define PG8_WAIT_V(n) asm volatile("s_waitcnt vmcnt(" #n ")" ::: "memory")
; #define PG8_WAIT_L(n) asm volatile("s_waitcnt lgkmcnt(" #n ")" ::: "memory")
; #define PG8_BAR __builtin_amdgcn_s_barrier()
; template <class Epi, class Sched, bool ALIGN_EPI = false, bool SP2 = false>
; __device__ __forceinline__ void gemm_phase(LAS unsigned char* lds, const Gemm g, const Sched& S, const Epi& E) {
;     ...
;             const bool last = (t == nt - 2);
;             const char* a1 = cA + (size_t)(t + 1) * kstep;
;             const char* a2 = last ? nA : cA + (size_t)(t + 2) * kstep; const char* b2 = last ? nB : cB + (size_t)(t + 2) * kstep;
;             const char* a3 = a2 + kstep; const char* b3 = b2 + kstep;
;             if (last && has_next) S.a_ready(nxt);
;             if constexpr (SP2) {
;             PG8_LDB(B0, 0, 0); PG8_LDB(B1, 0, 1); PG8_SCHED; PG8_LDA(At, 0, 0); PG8_STAGE(PG8_SA(1, 1), a1 + hstep, voffA);
;             PG8_WAIT_V(8); PG8_WAIT_L(0); PG8_BAR; PG8_MMA(0, 0, At, B0); PG8_MMA(0, 1, At, B1); PG8_BAR; PG8_SCHED;
;             PG8_LDA(At, 0, 1); PG8_STAGE(PG8_SB(0, 0), b2, voffB); PG8_STAGE(PG8_SB(0, 1), b2 + hstep, voffB); PG8_STAGE(PG8_SA(0, 0), a2, voffA);
;             PG8_WAIT_V(8); PG8_WAIT_L(0); PG8_BAR; PG8_MMA(1, 0, At, B0); PG8_MMA(1, 1, At, B1); PG8_BAR; PG8_SCHED;
.LBB0_257:
	s_add_u32 s24, s22, 0x100
	s_addc_u32 s25, s23, 0
	s_add_i32 s50, 0, 0x10000
	s_cmpk_eq_i32 s49, 0x54
	s_cselect_b32 s29, s1, s25
	s_cselect_b32 s28, s0, s24
	s_cselect_b32 s27, s21, s48
	s_cselect_b32 s26, s20, s47
	s_add_i32 s51, 0, 0x14000
	v_add_u32_e32 v126, s50, v247
	v_add_u32_e32 v158, s51, v247
	ds_read_b128 v[90:93], v126
	ds_read_b128 v[102:105], v126 offset:1024
	ds_read_b128 v[114:117], v126 offset:2048
	ds_read_b128 v[126:129], v126 offset:3072
	ds_read_b128 v[138:141], v158
	ds_read_b128 v[142:145], v158 offset:1024
	ds_read_b128 v[154:157], v158 offset:2048
	ds_read_b128 v[158:161], v158 offset:3072
	v_lshl_add_u64 v[186:187], s[22:23], 0, v[200:201]
	s_add_i32 m0, s6, 0xc000
	ds_read_b128 v[162:165], v249
	ds_read_b128 v[166:169], v249 offset:1024
	ds_read_b128 v[170:173], v249 offset:2048
	ds_read_b128 v[174:177], v249 offset:3072
	ds_read_b128 v[178:181], v249 offset:4096
	ds_read_b128 v[182:185], v249 offset:5120
	ds_read_b128 v[204:207], v249 offset:6144
	ds_read_b128 v[208:211], v249 offset:7168
	global_load_lds_dwordx4 v[186:187], off
	v_lshl_add_u64 v[186:187], s[22:23], 0, v[202:203]
	s_add_i32 m0, s6, 0xe000
	s_nop 0
	global_load_lds_dwordx4 v[186:187], off
	s_waitcnt vmcnt(8)
	s_waitcnt lgkmcnt(0)
	s_barrier
	s_setprio 1
	s_waitcnt lgkmcnt(0)
	v_mfma_f32_16x16x32_bf16 v[150:153], v[90:93], v[162:165], v[150:153]
	v_mfma_f32_16x16x32_bf16 v[150:153], v[102:105], v[166:169], v[150:153]
	v_mfma_f32_16x16x32_bf16 v[146:149], v[126:129], v[166:169], v[146:149]
	v_mfma_f32_16x16x32_bf16 v[146:149], v[114:117], v[162:165], v[146:149]
	v_mfma_f32_16x16x32_bf16 v[118:121], v[114:117], v[170:173], v[118:121]
	v_mfma_f32_16x16x32_bf16 v[118:121], v[126:129], v[174:177], v[118:121]
	v_mfma_f32_16x16x32_bf16 v[122:125], v[102:105], v[174:177], v[122:125]
	v_mfma_f32_16x16x32_bf16 v[122:125], v[90:93], v[170:173], v[122:125]
	v_mfma_f32_16x16x32_bf16 v[98:101], v[90:93], v[178:181], v[98:101]
	v_mfma_f32_16x16x32_bf16 v[98:101], v[102:105], v[182:185], v[98:101]
	v_mfma_f32_16x16x32_bf16 v[94:97], v[126:129], v[182:185], v[94:97]
	v_mfma_f32_16x16x32_bf16 v[94:97], v[114:117], v[178:181], v[94:97]
	v_mfma_f32_16x16x32_bf16 v[74:77], v[114:117], v[204:207], v[74:77]
	v_mfma_f32_16x16x32_bf16 v[74:77], v[126:129], v[208:211], v[74:77]
	v_mfma_f32_16x16x32_bf16 v[78:81], v[102:105], v[208:211], v[78:81]
	v_mfma_f32_16x16x32_bf16 v[78:81], v[90:93], v[204:207], v[78:81]
	s_setprio 0
	s_setprio 1
	v_mfma_f32_16x16x32_bf16 v[134:137], v[138:141], v[162:165], v[134:137]
	v_mfma_f32_16x16x32_bf16 v[134:137], v[142:145], v[166:169], v[134:137]
	v_mfma_f32_16x16x32_bf16 v[130:133], v[158:161], v[166:169], v[130:133]
	v_mfma_f32_16x16x32_bf16 v[130:133], v[154:157], v[162:165], v[130:133]
	v_mfma_f32_16x16x32_bf16 v[106:109], v[154:157], v[170:173], v[106:109]
	v_mfma_f32_16x16x32_bf16 v[106:109], v[158:161], v[174:177], v[106:109]
	v_mfma_f32_16x16x32_bf16 v[110:113], v[142:145], v[174:177], v[110:113]
	v_mfma_f32_16x16x32_bf16 v[110:113], v[138:141], v[170:173], v[110:113]
	v_mfma_f32_16x16x32_bf16 v[86:89], v[138:141], v[178:181], v[86:89]
	v_mfma_f32_16x16x32_bf16 v[86:89], v[142:145], v[182:185], v[86:89]
	v_mfma_f32_16x16x32_bf16 v[82:85], v[158:161], v[182:185], v[82:85]
	v_mfma_f32_16x16x32_bf16 v[82:85], v[154:157], v[178:181], v[82:85]
	v_mfma_f32_16x16x32_bf16 v[66:69], v[154:157], v[204:207], v[66:69]
	v_mfma_f32_16x16x32_bf16 v[66:69], v[158:161], v[208:211], v[66:69]
	v_mfma_f32_16x16x32_bf16 v[70:73], v[142:145], v[208:211], v[70:73]
	v_mfma_f32_16x16x32_bf16 v[70:73], v[138:141], v[204:207], v[70:73]
	s_setprio 0
	s_barrier
	s_add_i32 s22, s50, s2
	v_lshl_add_u64 v[186:187], s[26:27], 0, v[0:1]
	s_mov_b32 m0, s22
	ds_read_b128 v[162:165], v249 offset:16384
	ds_read_b128 v[166:169], v249 offset:17408
	ds_read_b128 v[170:173], v249 offset:18432
	ds_read_b128 v[174:177], v249 offset:19456
	ds_read_b128 v[178:181], v249 offset:20480
	ds_read_b128 v[182:185], v249 offset:21504
	ds_read_b128 v[204:207], v249 offset:22528
	ds_read_b128 v[208:211], v249 offset:23552
	global_load_lds_dwordx4 v[186:187], off
	s_add_i32 m0, s22, 0x2000
	s_add_u32 s22, s26, 0x160000
	v_lshl_add_u64 v[188:189], s[26:27], 0, v[194:195]
	s_addc_u32 s23, s27, 0
	s_add_i32 s50, s51, s2
	global_load_lds_dwordx4 v[188:189], off
	v_lshl_add_u64 v[190:191], s[22:23], 0, v[0:1]
	s_mov_b32 m0, s50
	v_lshl_add_u64 v[192:193], s[28:29], 0, v[196:197]
	global_load_lds_dwordx4 v[190:191], off
	v_lshl_add_u64 v[190:191], s[22:23], 0, v[194:195]
	s_add_i32 m0, s50, 0x2000
	s_nop 0
	global_load_lds_dwordx4 v[190:191], off
	v_lshl_add_u64 v[190:191], s[28:29], 0, v[198:199]
	s_mov_b32 m0, s6
	s_nop 0
	global_load_lds_dwordx4 v[190:191], off
	s_mov_b32 m0, s7
	s_nop 0
	global_load_lds_dwordx4 v[192:193], off
	s_waitcnt vmcnt(8)
	s_waitcnt lgkmcnt(0)
	s_barrier
; #define PG8_STAGE(bufoff, gbase, voff) do { _Pragma("unroll") for (int _i = 0; _i < 2; ++_i) \
;         __builtin_amdgcn_global_load_lds((const unsigned*)((const char*)(gbase) + (voff)[_i]), (LAS unsigned*)(lds + (bufoff) + ldsw + _i * 8192), 16, 0, 0); } while (0)
; #define PG8_LDA(dst, b, h) do { _Pragma("unroll") for (int m = 0; m < 4; ++m) _Pragma("unroll") for (int k = 0; k < 2; ++k) dst[m][k] = *(const LAS bf16x8*)(lds + PG8_SA(b, h) + aoff + m * 2048 + k * 1024); } while (0)
; #define PG8_LDB(dst, b, h) do { _Pragma("unroll") for (int n = 0; n < 2; ++n) _Pragma("unroll") for (int k = 0; k < 2; ++k) dst[n][k] = *(const LAS bf16x8*)(lds + PG8_SB(b, h) + boff + n * 2048 + k * 1024); } while (0)
; #define PG8_MMA(ai, bj, At, Bt) do { __builtin_amdgcn_s_setprio(1); _Pragma("unroll") for (int m = 0; m < 4; ++m) _Pragma("unroll") for (int n = 0; n < 2; ++n) _Pragma("unroll") for (int k = 0; k < 2; ++k) \
;         acc[ai][bj][m][n] = __builtin_amdgcn_mfma_f32_16x16x32_bf16(Bt[n][k], At[m][k], acc[ai][bj][m][n], 0, 0, 0); __builtin_amdgcn_s_setprio(0); } while (0)
; #define PG8_WAIT_V(n) asm volatile("s_waitcnt vmcnt(" #n ")" ::: "memory")
; #define PG8_WAIT_L(n) asm volatile("s_waitcnt lgkmcnt(" #n ")" ::: "memory")
; #define PG8_BAR __builtin_amdgcn_s_barrier()
; #define PG8_SCHED __builtin_amdgcn_sched_barrier(0)
; template <class Epi, class Sched, bool ALIGN_EPI = false, bool SP2 = false>
; __device__ __forceinline__ void gemm_phase(LAS unsigned char* lds, const Gemm g, const Sched& S, const Epi& E) {
;     ...
;             PG8_WAIT_V(8); PG8_WAIT_L(0); PG8_BAR; PG8_MMA(1, 0, At, B0); PG8_MMA(1, 1, At, B1); PG8_BAR; PG8_SCHED;
;             PG8_LDB(B0, 1, 0); PG8_LDB(B1, 1, 1); PG8_SCHED; PG8_LDA(At, 1, 0); PG8_STAGE(PG8_SA(0, 1), a2 + hstep, voffA);
;             PG8_WAIT_V(8); PG8_WAIT_L(0); PG8_BAR; PG8_MMA(0, 0, At, B0); PG8_MMA(0, 1, At, B1); PG8_BAR; PG8_SCHED;
	s_setprio 1
	s_waitcnt lgkmcnt(0)
	v_mfma_f32_16x16x32_bf16 v[62:65], v[90:93], v[162:165], v[62:65]
	v_mfma_f32_16x16x32_bf16 v[62:65], v[102:105], v[166:169], v[62:65]
	v_mfma_f32_16x16x32_bf16 v[58:61], v[126:129], v[166:169], v[58:61]
	v_mfma_f32_16x16x32_bf16 v[58:61], v[114:117], v[162:165], v[58:61]
	v_mfma_f32_16x16x32_bf16 v[42:45], v[114:117], v[170:173], v[42:45]
	v_mfma_f32_16x16x32_bf16 v[42:45], v[126:129], v[174:177], v[42:45]
	v_mfma_f32_16x16x32_bf16 v[46:49], v[102:105], v[174:177], v[46:49]
	v_mfma_f32_16x16x32_bf16 v[46:49], v[90:93], v[170:173], v[46:49]
	v_mfma_f32_16x16x32_bf16 v[30:33], v[90:93], v[178:181], v[30:33]
	v_mfma_f32_16x16x32_bf16 v[30:33], v[102:105], v[182:185], v[30:33]
	v_mfma_f32_16x16x32_bf16 v[26:29], v[126:129], v[182:185], v[26:29]
	v_mfma_f32_16x16x32_bf16 v[26:29], v[114:117], v[178:181], v[26:29]
	v_mfma_f32_16x16x32_bf16 v[10:13], v[114:117], v[204:207], v[10:13]
	v_mfma_f32_16x16x32_bf16 v[10:13], v[126:129], v[208:211], v[10:13]
	v_mfma_f32_16x16x32_bf16 v[14:17], v[102:105], v[208:211], v[14:17]
	v_mfma_f32_16x16x32_bf16 v[14:17], v[90:93], v[204:207], v[14:17]
	s_setprio 0
	s_setprio 1
	v_mfma_f32_16x16x32_bf16 v[54:57], v[138:141], v[162:165], v[54:57]
	v_mfma_f32_16x16x32_bf16 v[54:57], v[142:145], v[166:169], v[54:57]
	v_mfma_f32_16x16x32_bf16 v[50:53], v[158:161], v[166:169], v[50:53]
	v_mfma_f32_16x16x32_bf16 v[50:53], v[154:157], v[162:165], v[50:53]
	v_mfma_f32_16x16x32_bf16 v[34:37], v[154:157], v[170:173], v[34:37]
	v_mfma_f32_16x16x32_bf16 v[34:37], v[158:161], v[174:177], v[34:37]
	v_mfma_f32_16x16x32_bf16 v[38:41], v[142:145], v[174:177], v[38:41]
	v_mfma_f32_16x16x32_bf16 v[38:41], v[138:141], v[170:173], v[38:41]
	v_mfma_f32_16x16x32_bf16 v[22:25], v[138:141], v[178:181], v[22:25]
	v_mfma_f32_16x16x32_bf16 v[22:25], v[142:145], v[182:185], v[22:25]
	v_mfma_f32_16x16x32_bf16 v[18:21], v[158:161], v[182:185], v[18:21]
	v_mfma_f32_16x16x32_bf16 v[18:21], v[154:157], v[178:181], v[18:21]
	v_mfma_f32_16x16x32_bf16 v[2:5], v[154:157], v[204:207], v[2:5]
	v_mfma_f32_16x16x32_bf16 v[2:5], v[158:161], v[208:211], v[2:5]
	v_mfma_f32_16x16x32_bf16 v[6:9], v[142:145], v[208:211], v[6:9]
	v_mfma_f32_16x16x32_bf16 v[6:9], v[138:141], v[204:207], v[6:9]
	s_setprio 0
	s_barrier
	s_add_i32 s50, 0, 0x18000
	s_add_i32 s51, 0, 0x1c000
	v_add_u32_e32 v126, s50, v247
	v_add_u32_e32 v158, s51, v247
	ds_read_b128 v[90:93], v126
	ds_read_b128 v[102:105], v126 offset:1024
	ds_read_b128 v[114:117], v126 offset:2048
	ds_read_b128 v[126:129], v126 offset:3072
	ds_read_b128 v[138:141], v158
	ds_read_b128 v[142:145], v158 offset:1024
	ds_read_b128 v[154:157], v158 offset:2048
	ds_read_b128 v[158:161], v158 offset:3072
	s_add_u32 s22, s28, 0x160000
	s_addc_u32 s23, s29, 0
	s_mov_b32 m0, s8
	v_lshl_add_u64 v[212:213], s[22:23], 0, v[198:199]
	ds_read_b128 v[162:165], v249 offset:32768
	ds_read_b128 v[166:169], v249 offset:33792
	ds_read_b128 v[170:173], v249 offset:34816
	ds_read_b128 v[174:177], v249 offset:35840
	ds_read_b128 v[178:181], v249 offset:36864
	ds_read_b128 v[182:185], v249 offset:37888
	ds_read_b128 v[204:207], v249 offset:38912
	ds_read_b128 v[208:211], v249 offset:39936
	global_load_lds_dwordx4 v[212:213], off
	v_lshl_add_u64 v[212:213], s[22:23], 0, v[196:197]
	s_mov_b32 m0, s31
	s_nop 0
	global_load_lds_dwordx4 v[212:213], off
	s_waitcnt vmcnt(8)
	s_waitcnt lgkmcnt(0)
	s_barrier
	s_setprio 1
	s_waitcnt lgkmcnt(0)
	v_mfma_f32_16x16x32_bf16 v[150:153], v[90:93], v[162:165], v[150:153]
	v_mfma_f32_16x16x32_bf16 v[150:153], v[102:105], v[166:169], v[150:153]
	v_mfma_f32_16x16x32_bf16 v[146:149], v[126:129], v[166:169], v[146:149]
	v_mfma_f32_16x16x32_bf16 v[146:149], v[114:117], v[162:165], v[146:149]
	v_mfma_f32_16x16x32_bf16 v[118:121], v[114:117], v[170:173], v[118:121]
	v_mfma_f32_16x16x32_bf16 v[118:121], v[126:129], v[174:177], v[118:121]
	v_mfma_f32_16x16x32_bf16 v[122:125], v[102:105], v[174:177], v[122:125]
	v_mfma_f32_16x16x32_bf16 v[122:125], v[90:93], v[170:173], v[122:125]
	v_mfma_f32_16x16x32_bf16 v[98:101], v[90:93], v[178:181], v[98:101]
	v_mfma_f32_16x16x32_bf16 v[98:101], v[102:105], v[182:185], v[98:101]
	v_mfma_f32_16x16x32_bf16 v[94:97], v[126:129], v[182:185], v[94:97]
	v_mfma_f32_16x16x32_bf16 v[94:97], v[114:117], v[178:181], v[94:97]
	v_mfma_f32_16x16x32_bf16 v[74:77], v[114:117], v[204:207], v[74:77]
	v_mfma_f32_16x16x32_bf16 v[74:77], v[126:129], v[208:211], v[74:77]
	v_mfma_f32_16x16x32_bf16 v[78:81], v[102:105], v[208:211], v[78:81]
	v_mfma_f32_16x16x32_bf16 v[78:81], v[90:93], v[204:207], v[78:81]
	s_setprio 0
	s_setprio 1
	v_mfma_f32_16x16x32_bf16 v[134:137], v[138:141], v[162:165], v[134:137]
	v_mfma_f32_16x16x32_bf16 v[134:137], v[142:145], v[166:169], v[134:137]
	v_mfma_f32_16x16x32_bf16 v[130:133], v[158:161], v[166:169], v[130:133]
	v_mfma_f32_16x16x32_bf16 v[130:133], v[154:157], v[162:165], v[130:133]
	v_mfma_f32_16x16x32_bf16 v[106:109], v[154:157], v[170:173], v[106:109]
	v_mfma_f32_16x16x32_bf16 v[106:109], v[158:161], v[174:177], v[106:109]
	v_mfma_f32_16x16x32_bf16 v[110:113], v[142:145], v[174:177], v[110:113]
	v_mfma_f32_16x16x32_bf16 v[110:113], v[138:141], v[170:173], v[110:113]
	v_mfma_f32_16x16x32_bf16 v[86:89], v[138:141], v[178:181], v[86:89]
	v_mfma_f32_16x16x32_bf16 v[86:89], v[142:145], v[182:185], v[86:89]
	v_mfma_f32_16x16x32_bf16 v[82:85], v[158:161], v[182:185], v[82:85]
	v_mfma_f32_16x16x32_bf16 v[82:85], v[154:157], v[178:181], v[82:85]
	v_mfma_f32_16x16x32_bf16 v[66:69], v[154:157], v[204:207], v[66:69]
	v_mfma_f32_16x16x32_bf16 v[66:69], v[158:161], v[208:211], v[66:69]
	v_mfma_f32_16x16x32_bf16 v[70:73], v[142:145], v[208:211], v[70:73]
	v_mfma_f32_16x16x32_bf16 v[70:73], v[138:141], v[204:207], v[70:73]
	s_setprio 0
	s_barrier
; #define PG8_STAGE(bufoff, gbase, voff) do { _Pragma("unroll") for (int _i = 0; _i < 2; ++_i) \
;         __builtin_amdgcn_global_load_lds((const unsigned*)((const char*)(gbase) + (voff)[_i]), (LAS unsigned*)(lds + (bufoff) + ldsw + _i * 8192), 16, 0, 0); } while (0)
; #define PG8_LDA(dst, b, h) do { _Pragma("unroll") for (int m = 0; m < 4; ++m) _Pragma("unroll") for (int k = 0; k < 2; ++k) dst[m][k] = *(const LAS bf16x8*)(lds + PG8_SA(b, h) + aoff + m * 2048 + k * 1024); } while (0)
; #define PG8_MMA(ai, bj, At, Bt) do { __builtin_amdgcn_s_setprio(1); _Pragma("unroll") for (int m = 0; m < 4; ++m) _Pragma("unroll") for (int n = 0; n < 2; ++n) _Pragma("unroll") for (int k = 0; k < 2; ++k) \
;         acc[ai][bj][m][n] = __builtin_amdgcn_mfma_f32_16x16x32_bf16(Bt[n][k], At[m][k], acc[ai][bj][m][n], 0, 0, 0); __builtin_amdgcn_s_setprio(0); } while (0)
; #define PG8_WAIT_V(n) asm volatile("s_waitcnt vmcnt(" #n ")" ::: "memory")
; #define PG8_WAIT_L(n) asm volatile("s_waitcnt lgkmcnt(" #n ")" ::: "memory")
; #define PG8_BAR __builtin_amdgcn_s_barrier()
; #define PG8_SCHED __builtin_amdgcn_sched_barrier(0)
; template <class Epi, class Sched, bool ALIGN_EPI = false, bool SP2 = false>
; __device__ __forceinline__ void gemm_phase(LAS unsigned char* lds, const Gemm g, const Sched& S, const Epi& E) {
;     ...
;             PG8_LDA(At, 1, 1); PG8_STAGE(PG8_SB(1, 0), b3, voffB); PG8_STAGE(PG8_SB(1, 1), b3 + hstep, voffB); PG8_STAGE(PG8_SA(1, 0), a3, voffA);
;             PG8_WAIT_V(8); PG8_WAIT_L(0); PG8_BAR; PG8_MMA(1, 0, At, B0); PG8_MMA(1, 1, At, B1); PG8_BAR; PG8_SCHED;
;     ...
;         if constexpr (ALIGN_EPI) { if (wr == 0) PG8_BAR; }
	s_add_i32 s22, s50, s2
	v_lshl_add_u64 v[186:187], v[186:187], 0, s[12:13]
	s_mov_b32 m0, s22
	ds_read_b128 v[162:165], v249 offset:49152
	ds_read_b128 v[166:169], v249 offset:50176
	ds_read_b128 v[170:173], v249 offset:51200
	ds_read_b128 v[174:177], v249 offset:52224
	ds_read_b128 v[178:181], v249 offset:53248
	ds_read_b128 v[182:185], v249 offset:54272
	ds_read_b128 v[204:207], v249 offset:55296
	ds_read_b128 v[208:211], v249 offset:56320
	global_load_lds_dwordx4 v[186:187], off
	s_add_i32 m0, s22, 0x2000
	s_add_u32 s22, s26, 0x160080
	v_lshl_add_u64 v[186:187], v[188:189], 0, s[12:13]
	s_addc_u32 s23, s27, 0
	s_add_i32 s26, s51, s2
	global_load_lds_dwordx4 v[186:187], off
	v_lshl_add_u64 v[186:187], s[22:23], 0, v[0:1]
	s_mov_b32 m0, s26
	s_nop 0
	global_load_lds_dwordx4 v[186:187], off
	v_lshl_add_u64 v[186:187], s[22:23], 0, v[194:195]
	s_add_i32 m0, s26, 0x2000
	s_nop 0
	global_load_lds_dwordx4 v[186:187], off
	v_lshl_add_u64 v[186:187], v[190:191], 0, s[12:13]
	s_mov_b32 m0, s35
	s_nop 0
	global_load_lds_dwordx4 v[186:187], off
	v_lshl_add_u64 v[186:187], v[192:193], 0, s[12:13]
	s_mov_b32 m0, s40
	s_nop 0
	global_load_lds_dwordx4 v[186:187], off
	s_waitcnt vmcnt(8)
	s_waitcnt lgkmcnt(0)
	s_barrier
	s_setprio 1
	s_waitcnt lgkmcnt(0)
	v_mfma_f32_16x16x32_bf16 v[62:65], v[90:93], v[162:165], v[62:65]
	v_mfma_f32_16x16x32_bf16 v[62:65], v[102:105], v[166:169], v[62:65]
	v_mfma_f32_16x16x32_bf16 v[58:61], v[126:129], v[166:169], v[58:61]
	v_mfma_f32_16x16x32_bf16 v[58:61], v[114:117], v[162:165], v[58:61]
	v_mfma_f32_16x16x32_bf16 v[42:45], v[114:117], v[170:173], v[42:45]
	v_mfma_f32_16x16x32_bf16 v[42:45], v[126:129], v[174:177], v[42:45]
	v_mfma_f32_16x16x32_bf16 v[46:49], v[102:105], v[174:177], v[46:49]
	v_mfma_f32_16x16x32_bf16 v[46:49], v[90:93], v[170:173], v[46:49]
	v_mfma_f32_16x16x32_bf16 v[30:33], v[90:93], v[178:181], v[30:33]
	v_mfma_f32_16x16x32_bf16 v[30:33], v[102:105], v[182:185], v[30:33]
	v_mfma_f32_16x16x32_bf16 v[26:29], v[126:129], v[182:185], v[26:29]
	v_mfma_f32_16x16x32_bf16 v[26:29], v[114:117], v[178:181], v[26:29]
	v_mfma_f32_16x16x32_bf16 v[10:13], v[114:117], v[204:207], v[10:13]
	v_mfma_f32_16x16x32_bf16 v[10:13], v[126:129], v[208:211], v[10:13]
	v_mfma_f32_16x16x32_bf16 v[14:17], v[102:105], v[208:211], v[14:17]
	v_mfma_f32_16x16x32_bf16 v[14:17], v[90:93], v[204:207], v[14:17]
	s_setprio 0
	s_setprio 1
	v_mfma_f32_16x16x32_bf16 v[54:57], v[138:141], v[162:165], v[54:57]
	v_mfma_f32_16x16x32_bf16 v[54:57], v[142:145], v[166:169], v[54:57]
	v_mfma_f32_16x16x32_bf16 v[50:53], v[158:161], v[166:169], v[50:53]
	v_mfma_f32_16x16x32_bf16 v[50:53], v[154:157], v[162:165], v[50:53]
	v_mfma_f32_16x16x32_bf16 v[34:37], v[154:157], v[170:173], v[34:37]
	v_mfma_f32_16x16x32_bf16 v[34:37], v[158:161], v[174:177], v[34:37]
	v_mfma_f32_16x16x32_bf16 v[38:41], v[142:145], v[174:177], v[38:41]
	v_mfma_f32_16x16x32_bf16 v[38:41], v[138:141], v[170:173], v[38:41]
	v_mfma_f32_16x16x32_bf16 v[22:25], v[138:141], v[178:181], v[22:25]
	v_mfma_f32_16x16x32_bf16 v[22:25], v[142:145], v[182:185], v[22:25]
	v_mfma_f32_16x16x32_bf16 v[18:21], v[158:161], v[182:185], v[18:21]
	v_mfma_f32_16x16x32_bf16 v[18:21], v[154:157], v[178:181], v[18:21]
	v_mfma_f32_16x16x32_bf16 v[2:5], v[154:157], v[204:207], v[2:5]
	v_mfma_f32_16x16x32_bf16 v[2:5], v[158:161], v[208:211], v[2:5]
	v_mfma_f32_16x16x32_bf16 v[6:9], v[142:145], v[208:211], v[6:9]
	v_mfma_f32_16x16x32_bf16 v[6:9], v[138:141], v[204:207], v[6:9]
	s_setprio 0
	s_barrier
	s_add_i32 s49, s49, 2
	s_add_u32 s47, s47, 0x100
	s_addc_u32 s48, s48, 0
	s_cmpk_gt_u32 s49, 0x55
	s_mov_b64 s[22:23], s[24:25]
	s_cbranch_scc0 .LBB0_257
	s_and_b64 vcc, exec, s[18:19]
	s_cbranch_vccz .LBB0_260
	s_barrier

; #define PG8_STAGE(bufoff, gbase, voff) do { _Pragma("unroll") for (int _i = 0; _i < 2; ++_i) \
;         __builtin_amdgcn_global_load_lds((const unsigned*)((const char*)(gbase) + (voff)[_i]), (LAS unsigned*)(lds + (bufoff) + ldsw + _i * 8192), 16, 0, 0); } while (0)
; #define PG8_LDA(dst, b, h) do { _Pragma("unroll") for (int m = 0; m < 4; ++m) _Pragma("unroll") for (int k = 0; k < 2; ++k) dst[m][k] = *(const LAS bf16x8*)(lds + PG8_SA(b, h) + aoff + m * 2048 + k * 1024); } while (0)
; #define PG8_LDB(dst, b, h) do { _Pragma("unroll") for (int n = 0; n < 2; ++n) _Pragma("unroll") for (int k = 0; k < 2; ++k) dst[n][k] = *(const LAS bf16x8*)(lds + PG8_SB(b, h) + boff + n * 2048 + k * 1024); } while (0)
; #define PG8_MMA(ai, bj, At, Bt) do { __builtin_amdgcn_s_setprio(1); _Pragma("unroll") for (int m = 0; m < 4; ++m) _Pragma("unroll") for (int n = 0; n < 2; ++n) _Pragma("unroll") for (int k = 0; k < 2; ++k) \
;         acc[ai][bj][m][n] = __builtin_amdgcn_mfma_f32_16x16x32_bf16(Bt[n][k], At[m][k], acc[ai][bj][m][n], 0, 0, 0); __builtin_amdgcn_s_setprio(0); } while (0)
; #define PG8_WAIT_V(n) asm volatile("s_waitcnt vmcnt(" #n ")" ::: "memory")
; #define PG8_WAIT_L(n) asm volatile("s_waitcnt lgkmcnt(" #n ")" ::: "memory")
; #define PG8_BAR __builtin_amdgcn_s_barrier()
; template <class Epi, class Sched, bool ALIGN_EPI = false, bool SP2 = false>
; __device__ __forceinline__ void gemm_phase(LAS unsigned char* lds, const Gemm g, const Sched& S, const Epi& E) {
;     ...
;             const bool last = (t == nt - 2);
;             const char* a1 = cA + (size_t)(t + 1) * kstep;
;             const char* a2 = last ? nA : cA + (size_t)(t + 2) * kstep; const char* b2 = last ? nB : cB + (size_t)(t + 2) * kstep;
;             const char* a3 = a2 + kstep; const char* b3 = b2 + kstep;
;             if (last && has_next) S.a_ready(nxt);
;             if constexpr (SP2) {
;             PG8_LDB(B0, 0, 0); PG8_LDB(B1, 0, 1); PG8_SCHED; PG8_LDA(At, 0, 0); PG8_STAGE(PG8_SA(1, 1), a1 + hstep, voffA);
;             PG8_WAIT_V(8); PG8_WAIT_L(0); PG8_BAR; PG8_MMA(0, 0, At, B0); PG8_MMA(0, 1, At, B1); PG8_BAR; PG8_SCHED;
;             PG8_LDA(At, 0, 1); PG8_STAGE(PG8_SB(0, 0), b2, voffB); PG8_STAGE(PG8_SB(0, 1), b2 + hstep, voffB); PG8_STAGE(PG8_SA(0, 0), a2, voffA);
;             PG8_WAIT_V(8); PG8_WAIT_L(0); PG8_BAR; PG8_MMA(1, 0, At, B0); PG8_MMA(1, 1, At, B1); PG8_BAR; PG8_SCHED;
.LBB0_359:
	s_add_u32 s28, s26, 0xfff80080
	s_addc_u32 s29, s27, -1
	s_add_i32 s41, 0, 0x10000
	s_cmp_eq_u32 s40, 28
	s_cselect_b32 s31, s6, s29
	s_cselect_b32 s30, s7, s28
	v_add_u32_e32 v0, s41, v159
	s_cselect_b32 s29, s8, s35
	s_cselect_b32 s28, s19, s21
	s_add_i32 s57, 0, 0x14000
	ds_read_b128 v[142:145], v0
	ds_read_b128 v[146:149], v0 offset:1024
	ds_read_b128 v[150:153], v0 offset:2048
	ds_read_b128 v[154:157], v0 offset:3072
	v_add_u32_e32 v0, s57, v159
	ds_read_b128 v[162:165], v0
	ds_read_b128 v[166:169], v0 offset:1024
	ds_read_b128 v[170:173], v0 offset:2048
	ds_read_b128 v[174:177], v0 offset:3072
	v_lshl_add_u64 v[210:211], s[26:27], 0, v[138:139]
	s_add_i32 m0, s44, 0xc000
	ds_read_b128 v[178:181], v161
	ds_read_b128 v[182:185], v161 offset:1024
	ds_read_b128 v[186:189], v161 offset:2048
	ds_read_b128 v[190:193], v161 offset:3072
	ds_read_b128 v[194:197], v161 offset:4096
	ds_read_b128 v[198:201], v161 offset:5120
	ds_read_b128 v[202:205], v161 offset:6144
	ds_read_b128 v[206:209], v161 offset:7168
	global_load_lds_dwordx4 v[210:211], off
	v_lshl_add_u64 v[210:211], s[26:27], 0, v[140:141]
	s_add_i32 m0, s44, 0xe000
	s_nop 0
	global_load_lds_dwordx4 v[210:211], off
	s_waitcnt vmcnt(8)
	s_waitcnt lgkmcnt(0)
	s_barrier
	s_setprio 1
	s_waitcnt lgkmcnt(0)
	v_mfma_f32_16x16x32_bf16 v[126:129], v[142:145], v[178:181], v[126:129]
	v_mfma_f32_16x16x32_bf16 v[126:129], v[146:149], v[182:185], v[126:129]
	v_mfma_f32_16x16x32_bf16 v[122:125], v[154:157], v[182:185], v[122:125]
	v_mfma_f32_16x16x32_bf16 v[122:125], v[150:153], v[178:181], v[122:125]
	v_mfma_f32_16x16x32_bf16 v[106:109], v[150:153], v[186:189], v[106:109]
	v_mfma_f32_16x16x32_bf16 v[106:109], v[154:157], v[190:193], v[106:109]
	v_mfma_f32_16x16x32_bf16 v[110:113], v[146:149], v[190:193], v[110:113]
	v_mfma_f32_16x16x32_bf16 v[110:113], v[142:145], v[186:189], v[110:113]
	v_mfma_f32_16x16x32_bf16 v[94:97], v[142:145], v[194:197], v[94:97]
	v_mfma_f32_16x16x32_bf16 v[94:97], v[146:149], v[198:201], v[94:97]
	v_mfma_f32_16x16x32_bf16 v[90:93], v[154:157], v[198:201], v[90:93]
	v_mfma_f32_16x16x32_bf16 v[90:93], v[150:153], v[194:197], v[90:93]
	v_mfma_f32_16x16x32_bf16 v[74:77], v[150:153], v[202:205], v[74:77]
	v_mfma_f32_16x16x32_bf16 v[74:77], v[154:157], v[206:209], v[74:77]
	v_mfma_f32_16x16x32_bf16 v[78:81], v[146:149], v[206:209], v[78:81]
	v_mfma_f32_16x16x32_bf16 v[78:81], v[142:145], v[202:205], v[78:81]
	s_setprio 0
	s_setprio 1
	v_mfma_f32_16x16x32_bf16 v[118:121], v[162:165], v[178:181], v[118:121]
	v_mfma_f32_16x16x32_bf16 v[118:121], v[166:169], v[182:185], v[118:121]
	v_mfma_f32_16x16x32_bf16 v[114:117], v[174:177], v[182:185], v[114:117]
	v_mfma_f32_16x16x32_bf16 v[114:117], v[170:173], v[178:181], v[114:117]
	v_mfma_f32_16x16x32_bf16 v[98:101], v[170:173], v[186:189], v[98:101]
	v_mfma_f32_16x16x32_bf16 v[98:101], v[174:177], v[190:193], v[98:101]
	v_mfma_f32_16x16x32_bf16 v[102:105], v[166:169], v[190:193], v[102:105]
	v_mfma_f32_16x16x32_bf16 v[102:105], v[162:165], v[186:189], v[102:105]
	v_mfma_f32_16x16x32_bf16 v[86:89], v[162:165], v[194:197], v[86:89]
	v_mfma_f32_16x16x32_bf16 v[86:89], v[166:169], v[198:201], v[86:89]
	v_mfma_f32_16x16x32_bf16 v[82:85], v[174:177], v[198:201], v[82:85]
	v_mfma_f32_16x16x32_bf16 v[82:85], v[170:173], v[194:197], v[82:85]
	v_mfma_f32_16x16x32_bf16 v[66:69], v[170:173], v[202:205], v[66:69]
	v_mfma_f32_16x16x32_bf16 v[66:69], v[174:177], v[206:209], v[66:69]
	v_mfma_f32_16x16x32_bf16 v[70:73], v[166:169], v[206:209], v[70:73]
	v_mfma_f32_16x16x32_bf16 v[70:73], v[162:165], v[202:205], v[70:73]
	s_setprio 0
	s_barrier
	s_add_i32 s41, s41, s9
	v_lshl_add_u64 v[210:211], s[28:29], 0, v[134:135]
	s_mov_b32 m0, s41
	ds_read_b128 v[178:181], v161 offset:16384
	ds_read_b128 v[182:185], v161 offset:17408
	ds_read_b128 v[186:189], v161 offset:18432
	ds_read_b128 v[190:193], v161 offset:19456
	ds_read_b128 v[194:197], v161 offset:20480
	ds_read_b128 v[198:201], v161 offset:21504
	ds_read_b128 v[202:205], v161 offset:22528
	ds_read_b128 v[206:209], v161 offset:23552
	global_load_lds_dwordx4 v[210:211], off
	s_add_i32 m0, s41, 0x2000
	s_add_u32 s58, s28, 0x80000
	v_lshl_add_u64 v[212:213], s[28:29], 0, v[130:131]
	s_addc_u32 s59, s29, 0
	s_add_i32 s41, s57, s9
	global_load_lds_dwordx4 v[212:213], off
	v_lshl_add_u64 v[214:215], s[58:59], 0, v[134:135]
	s_mov_b32 m0, s41
	v_lshl_add_u64 v[216:217], s[30:31], 0, v[132:133]
	global_load_lds_dwordx4 v[214:215], off
	v_lshl_add_u64 v[214:215], s[58:59], 0, v[130:131]
	s_add_i32 m0, s41, 0x2000
	s_nop 0
	global_load_lds_dwordx4 v[214:215], off
	v_lshl_add_u64 v[214:215], s[30:31], 0, v[136:137]
	s_mov_b32 m0, s44
	s_nop 0
	global_load_lds_dwordx4 v[214:215], off
	s_mov_b32 m0, s45
	s_nop 0
	global_load_lds_dwordx4 v[216:217], off
	s_waitcnt vmcnt(8)
	s_waitcnt lgkmcnt(0)
	s_barrier
; #define PG8_STAGE(bufoff, gbase, voff) do { _Pragma("unroll") for (int _i = 0; _i < 2; ++_i) \
;         __builtin_amdgcn_global_load_lds((const unsigned*)((const char*)(gbase) + (voff)[_i]), (LAS unsigned*)(lds + (bufoff) + ldsw + _i * 8192), 16, 0, 0); } while (0)
; #define PG8_LDA(dst, b, h) do { _Pragma("unroll") for (int m = 0; m < 4; ++m) _Pragma("unroll") for (int k = 0; k < 2; ++k) dst[m][k] = *(const LAS bf16x8*)(lds + PG8_SA(b, h) + aoff + m * 2048 + k * 1024); } while (0)
; #define PG8_LDB(dst, b, h) do { _Pragma("unroll") for (int n = 0; n < 2; ++n) _Pragma("unroll") for (int k = 0; k < 2; ++k) dst[n][k] = *(const LAS bf16x8*)(lds + PG8_SB(b, h) + boff + n * 2048 + k * 1024); } while (0)
; #define PG8_MMA(ai, bj, At, Bt) do { __builtin_amdgcn_s_setprio(1); _Pragma("unroll") for (int m = 0; m < 4; ++m) _Pragma("unroll") for (int n = 0; n < 2; ++n) _Pragma("unroll") for (int k = 0; k < 2; ++k) \
;         acc[ai][bj][m][n] = __builtin_amdgcn_mfma_f32_16x16x32_bf16(Bt[n][k], At[m][k], acc[ai][bj][m][n], 0, 0, 0); __builtin_amdgcn_s_setprio(0); } while (0)
; #define PG8_WAIT_V(n) asm volatile("s_waitcnt vmcnt(" #n ")" ::: "memory")
; #define PG8_WAIT_L(n) asm volatile("s_waitcnt lgkmcnt(" #n ")" ::: "memory")
; #define PG8_BAR __builtin_amdgcn_s_barrier()
; #define PG8_SCHED __builtin_amdgcn_sched_barrier(0)
; template <class Epi, class Sched, bool ALIGN_EPI = false, bool SP2 = false>
; __device__ __forceinline__ void gemm_phase(LAS unsigned char* lds, const Gemm g, const Sched& S, const Epi& E) {
;     ...
;             PG8_WAIT_V(8); PG8_WAIT_L(0); PG8_BAR; PG8_MMA(1, 0, At, B0); PG8_MMA(1, 1, At, B1); PG8_BAR; PG8_SCHED;
;             PG8_LDB(B0, 1, 0); PG8_LDB(B1, 1, 1); PG8_SCHED; PG8_LDA(At, 1, 0); PG8_STAGE(PG8_SA(0, 1), a2 + hstep, voffA);
;             PG8_WAIT_V(8); PG8_WAIT_L(0); PG8_BAR; PG8_MMA(0, 0, At, B0); PG8_MMA(0, 1, At, B1); PG8_BAR; PG8_SCHED;
	s_setprio 1
	s_waitcnt lgkmcnt(0)
	v_mfma_f32_16x16x32_bf16 v[62:65], v[142:145], v[178:181], v[62:65]
	v_mfma_f32_16x16x32_bf16 v[62:65], v[146:149], v[182:185], v[62:65]
	v_mfma_f32_16x16x32_bf16 v[58:61], v[154:157], v[182:185], v[58:61]
	v_mfma_f32_16x16x32_bf16 v[58:61], v[150:153], v[178:181], v[58:61]
	v_mfma_f32_16x16x32_bf16 v[42:45], v[150:153], v[186:189], v[42:45]
	v_mfma_f32_16x16x32_bf16 v[42:45], v[154:157], v[190:193], v[42:45]
	v_mfma_f32_16x16x32_bf16 v[46:49], v[146:149], v[190:193], v[46:49]
	v_mfma_f32_16x16x32_bf16 v[46:49], v[142:145], v[186:189], v[46:49]
	v_mfma_f32_16x16x32_bf16 v[30:33], v[142:145], v[194:197], v[30:33]
	v_mfma_f32_16x16x32_bf16 v[30:33], v[146:149], v[198:201], v[30:33]
	v_mfma_f32_16x16x32_bf16 v[26:29], v[154:157], v[198:201], v[26:29]
	v_mfma_f32_16x16x32_bf16 v[26:29], v[150:153], v[194:197], v[26:29]
	v_mfma_f32_16x16x32_bf16 v[10:13], v[150:153], v[202:205], v[10:13]
	v_mfma_f32_16x16x32_bf16 v[10:13], v[154:157], v[206:209], v[10:13]
	v_mfma_f32_16x16x32_bf16 v[14:17], v[146:149], v[206:209], v[14:17]
	v_mfma_f32_16x16x32_bf16 v[14:17], v[142:145], v[202:205], v[14:17]
	s_setprio 0
	s_setprio 1
	v_mfma_f32_16x16x32_bf16 v[54:57], v[162:165], v[178:181], v[54:57]
	v_mfma_f32_16x16x32_bf16 v[54:57], v[166:169], v[182:185], v[54:57]
	v_mfma_f32_16x16x32_bf16 v[50:53], v[174:177], v[182:185], v[50:53]
	v_mfma_f32_16x16x32_bf16 v[50:53], v[170:173], v[178:181], v[50:53]
	v_mfma_f32_16x16x32_bf16 v[34:37], v[170:173], v[186:189], v[34:37]
	v_mfma_f32_16x16x32_bf16 v[34:37], v[174:177], v[190:193], v[34:37]
	v_mfma_f32_16x16x32_bf16 v[38:41], v[166:169], v[190:193], v[38:41]
	v_mfma_f32_16x16x32_bf16 v[38:41], v[162:165], v[186:189], v[38:41]
	v_mfma_f32_16x16x32_bf16 v[22:25], v[162:165], v[194:197], v[22:25]
	v_mfma_f32_16x16x32_bf16 v[22:25], v[166:169], v[198:201], v[22:25]
	v_mfma_f32_16x16x32_bf16 v[18:21], v[174:177], v[198:201], v[18:21]
	v_mfma_f32_16x16x32_bf16 v[18:21], v[170:173], v[194:197], v[18:21]
	v_mfma_f32_16x16x32_bf16 v[2:5], v[170:173], v[202:205], v[2:5]
	v_mfma_f32_16x16x32_bf16 v[2:5], v[174:177], v[206:209], v[2:5]
	v_mfma_f32_16x16x32_bf16 v[6:9], v[166:169], v[206:209], v[6:9]
	v_mfma_f32_16x16x32_bf16 v[6:9], v[162:165], v[202:205], v[6:9]
	s_setprio 0
	s_barrier
	s_add_i32 s41, 0, 0x18000
	v_add_u32_e32 v0, s41, v159
	s_add_i32 s57, 0, 0x1c000
	ds_read_b128 v[142:145], v0
	ds_read_b128 v[146:149], v0 offset:1024
	ds_read_b128 v[150:153], v0 offset:2048
	ds_read_b128 v[154:157], v0 offset:3072
	v_add_u32_e32 v0, s57, v159
	ds_read_b128 v[162:165], v0
	ds_read_b128 v[166:169], v0 offset:1024
	ds_read_b128 v[170:173], v0 offset:2048
	ds_read_b128 v[174:177], v0 offset:3072
	s_add_u32 s30, s30, 0x80000
	s_addc_u32 s31, s31, 0
	s_mov_b32 m0, s47
	v_lshl_add_u64 v[218:219], s[30:31], 0, v[136:137]
	ds_read_b128 v[178:181], v161 offset:32768
	ds_read_b128 v[182:185], v161 offset:33792
	ds_read_b128 v[186:189], v161 offset:34816
	ds_read_b128 v[190:193], v161 offset:35840
	ds_read_b128 v[194:197], v161 offset:36864
	ds_read_b128 v[198:201], v161 offset:37888
	ds_read_b128 v[202:205], v161 offset:38912
	ds_read_b128 v[206:209], v161 offset:39936
	global_load_lds_dwordx4 v[218:219], off
	v_lshl_add_u64 v[218:219], s[30:31], 0, v[132:133]
	s_mov_b32 m0, s48
	s_nop 0
	global_load_lds_dwordx4 v[218:219], off
	s_waitcnt vmcnt(8)
	s_waitcnt lgkmcnt(0)
	s_barrier
	s_setprio 1
	s_waitcnt lgkmcnt(0)
	v_mfma_f32_16x16x32_bf16 v[126:129], v[142:145], v[178:181], v[126:129]
	v_mfma_f32_16x16x32_bf16 v[126:129], v[146:149], v[182:185], v[126:129]
	v_mfma_f32_16x16x32_bf16 v[122:125], v[154:157], v[182:185], v[122:125]
	v_mfma_f32_16x16x32_bf16 v[122:125], v[150:153], v[178:181], v[122:125]
	v_mfma_f32_16x16x32_bf16 v[106:109], v[150:153], v[186:189], v[106:109]
	v_mfma_f32_16x16x32_bf16 v[106:109], v[154:157], v[190:193], v[106:109]
	v_mfma_f32_16x16x32_bf16 v[110:113], v[146:149], v[190:193], v[110:113]
	v_mfma_f32_16x16x32_bf16 v[110:113], v[142:145], v[186:189], v[110:113]
	v_mfma_f32_16x16x32_bf16 v[94:97], v[142:145], v[194:197], v[94:97]
	v_mfma_f32_16x16x32_bf16 v[94:97], v[146:149], v[198:201], v[94:97]
	v_mfma_f32_16x16x32_bf16 v[90:93], v[154:157], v[198:201], v[90:93]
	v_mfma_f32_16x16x32_bf16 v[90:93], v[150:153], v[194:197], v[90:93]
	v_mfma_f32_16x16x32_bf16 v[74:77], v[150:153], v[202:205], v[74:77]
	v_mfma_f32_16x16x32_bf16 v[74:77], v[154:157], v[206:209], v[74:77]
	v_mfma_f32_16x16x32_bf16 v[78:81], v[146:149], v[206:209], v[78:81]
	v_mfma_f32_16x16x32_bf16 v[78:81], v[142:145], v[202:205], v[78:81]
	s_setprio 0
	s_setprio 1
	v_mfma_f32_16x16x32_bf16 v[118:121], v[162:165], v[178:181], v[118:121]
	v_mfma_f32_16x16x32_bf16 v[118:121], v[166:169], v[182:185], v[118:121]
	v_mfma_f32_16x16x32_bf16 v[114:117], v[174:177], v[182:185], v[114:117]
	v_mfma_f32_16x16x32_bf16 v[114:117], v[170:173], v[178:181], v[114:117]
	v_mfma_f32_16x16x32_bf16 v[98:101], v[170:173], v[186:189], v[98:101]
	v_mfma_f32_16x16x32_bf16 v[98:101], v[174:177], v[190:193], v[98:101]
	v_mfma_f32_16x16x32_bf16 v[102:105], v[166:169], v[190:193], v[102:105]
	v_mfma_f32_16x16x32_bf16 v[102:105], v[162:165], v[186:189], v[102:105]
	v_mfma_f32_16x16x32_bf16 v[86:89], v[162:165], v[194:197], v[86:89]
	v_mfma_f32_16x16x32_bf16 v[86:89], v[166:169], v[198:201], v[86:89]
	v_mfma_f32_16x16x32_bf16 v[82:85], v[174:177], v[198:201], v[82:85]
	v_mfma_f32_16x16x32_bf16 v[82:85], v[170:173], v[194:197], v[82:85]
	v_mfma_f32_16x16x32_bf16 v[66:69], v[170:173], v[202:205], v[66:69]
	v_mfma_f32_16x16x32_bf16 v[66:69], v[174:177], v[206:209], v[66:69]
	v_mfma_f32_16x16x32_bf16 v[70:73], v[166:169], v[206:209], v[70:73]
	v_mfma_f32_16x16x32_bf16 v[70:73], v[162:165], v[202:205], v[70:73]
	s_setprio 0
	s_barrier
; #define PG8_STAGE(bufoff, gbase, voff) do { _Pragma("unroll") for (int _i = 0; _i < 2; ++_i) \
;         __builtin_amdgcn_global_load_lds((const unsigned*)((const char*)(gbase) + (voff)[_i]), (LAS unsigned*)(lds + (bufoff) + ldsw + _i * 8192), 16, 0, 0); } while (0)
; #define PG8_LDA(dst, b, h) do { _Pragma("unroll") for (int m = 0; m < 4; ++m) _Pragma("unroll") for (int k = 0; k < 2; ++k) dst[m][k] = *(const LAS bf16x8*)(lds + PG8_SA(b, h) + aoff + m * 2048 + k * 1024); } while (0)
; #define PG8_MMA(ai, bj, At, Bt) do { __builtin_amdgcn_s_setprio(1); _Pragma("unroll") for (int m = 0; m < 4; ++m) _Pragma("unroll") for (int n = 0; n < 2; ++n) _Pragma("unroll") for (int k = 0; k < 2; ++k) \
;         acc[ai][bj][m][n] = __builtin_amdgcn_mfma_f32_16x16x32_bf16(Bt[n][k], At[m][k], acc[ai][bj][m][n], 0, 0, 0); __builtin_amdgcn_s_setprio(0); } while (0)
; #define PG8_WAIT_V(n) asm volatile("s_waitcnt vmcnt(" #n ")" ::: "memory")
; #define PG8_WAIT_L(n) asm volatile("s_waitcnt lgkmcnt(" #n ")" ::: "memory")
; #define PG8_BAR __builtin_amdgcn_s_barrier()
; #define PG8_SCHED __builtin_amdgcn_sched_barrier(0)
; template <class Epi, class Sched, bool ALIGN_EPI = false, bool SP2 = false>
; __device__ __forceinline__ void gemm_phase(LAS unsigned char* lds, const Gemm g, const Sched& S, const Epi& E) {
;     ...
;             PG8_LDA(At, 1, 1); PG8_STAGE(PG8_SB(1, 0), b3, voffB); PG8_STAGE(PG8_SB(1, 1), b3 + hstep, voffB); PG8_STAGE(PG8_SA(1, 0), a3, voffA);
;             PG8_WAIT_V(8); PG8_WAIT_L(0); PG8_BAR; PG8_MMA(1, 0, At, B0); PG8_MMA(1, 1, At, B1); PG8_BAR; PG8_SCHED;
;     ...
;         if constexpr (ALIGN_EPI) { if (wr == 0) PG8_BAR; }
	s_add_i32 s30, s41, s9
	v_lshl_add_u64 v[210:211], v[210:211], 0, s[12:13]
	s_mov_b32 m0, s30
	ds_read_b128 v[178:181], v161 offset:49152
	ds_read_b128 v[182:185], v161 offset:50176
	ds_read_b128 v[186:189], v161 offset:51200
	ds_read_b128 v[190:193], v161 offset:52224
	ds_read_b128 v[194:197], v161 offset:53248
	ds_read_b128 v[198:201], v161 offset:54272
	ds_read_b128 v[202:205], v161 offset:55296
	ds_read_b128 v[206:209], v161 offset:56320
	global_load_lds_dwordx4 v[210:211], off
	s_add_i32 m0, s30, 0x2000
	s_add_u32 s28, s28, 0x80080
	v_lshl_add_u64 v[210:211], v[212:213], 0, s[12:13]
	s_addc_u32 s29, s29, 0
	s_add_i32 s30, s57, s9
	global_load_lds_dwordx4 v[210:211], off
	v_lshl_add_u64 v[210:211], s[28:29], 0, v[134:135]
	s_mov_b32 m0, s30
	s_nop 0
	global_load_lds_dwordx4 v[210:211], off
	v_lshl_add_u64 v[210:211], s[28:29], 0, v[130:131]
	s_add_i32 m0, s30, 0x2000
	s_nop 0
	global_load_lds_dwordx4 v[210:211], off
	v_lshl_add_u64 v[210:211], v[214:215], 0, s[12:13]
	s_mov_b32 m0, s53
	s_nop 0
	global_load_lds_dwordx4 v[210:211], off
	v_lshl_add_u64 v[210:211], v[216:217], 0, s[12:13]
	s_mov_b32 m0, s54
	s_nop 0
	global_load_lds_dwordx4 v[210:211], off
	s_waitcnt vmcnt(8)
	s_waitcnt lgkmcnt(0)
	s_barrier
	s_setprio 1
	s_waitcnt lgkmcnt(0)
	v_mfma_f32_16x16x32_bf16 v[62:65], v[142:145], v[178:181], v[62:65]
	v_mfma_f32_16x16x32_bf16 v[62:65], v[146:149], v[182:185], v[62:65]
	v_mfma_f32_16x16x32_bf16 v[58:61], v[154:157], v[182:185], v[58:61]
	v_mfma_f32_16x16x32_bf16 v[58:61], v[150:153], v[178:181], v[58:61]
	v_mfma_f32_16x16x32_bf16 v[42:45], v[150:153], v[186:189], v[42:45]
	v_mfma_f32_16x16x32_bf16 v[42:45], v[154:157], v[190:193], v[42:45]
	v_mfma_f32_16x16x32_bf16 v[46:49], v[146:149], v[190:193], v[46:49]
	v_mfma_f32_16x16x32_bf16 v[46:49], v[142:145], v[186:189], v[46:49]
	v_mfma_f32_16x16x32_bf16 v[30:33], v[142:145], v[194:197], v[30:33]
	v_mfma_f32_16x16x32_bf16 v[30:33], v[146:149], v[198:201], v[30:33]
	v_mfma_f32_16x16x32_bf16 v[26:29], v[154:157], v[198:201], v[26:29]
	v_mfma_f32_16x16x32_bf16 v[26:29], v[150:153], v[194:197], v[26:29]
	v_mfma_f32_16x16x32_bf16 v[10:13], v[150:153], v[202:205], v[10:13]
	v_mfma_f32_16x16x32_bf16 v[10:13], v[154:157], v[206:209], v[10:13]
	v_mfma_f32_16x16x32_bf16 v[14:17], v[146:149], v[206:209], v[14:17]
	v_mfma_f32_16x16x32_bf16 v[14:17], v[142:145], v[202:205], v[14:17]
	s_setprio 0
	s_setprio 1
	v_mfma_f32_16x16x32_bf16 v[54:57], v[162:165], v[178:181], v[54:57]
	v_mfma_f32_16x16x32_bf16 v[54:57], v[166:169], v[182:185], v[54:57]
	v_mfma_f32_16x16x32_bf16 v[50:53], v[174:177], v[182:185], v[50:53]
	v_mfma_f32_16x16x32_bf16 v[50:53], v[170:173], v[178:181], v[50:53]
	v_mfma_f32_16x16x32_bf16 v[34:37], v[170:173], v[186:189], v[34:37]
	v_mfma_f32_16x16x32_bf16 v[34:37], v[174:177], v[190:193], v[34:37]
	v_mfma_f32_16x16x32_bf16 v[38:41], v[166:169], v[190:193], v[38:41]
	v_mfma_f32_16x16x32_bf16 v[38:41], v[162:165], v[186:189], v[38:41]
	v_mfma_f32_16x16x32_bf16 v[22:25], v[162:165], v[194:197], v[22:25]
	v_mfma_f32_16x16x32_bf16 v[22:25], v[166:169], v[198:201], v[22:25]
	v_mfma_f32_16x16x32_bf16 v[18:21], v[174:177], v[198:201], v[18:21]
	v_mfma_f32_16x16x32_bf16 v[18:21], v[170:173], v[194:197], v[18:21]
	v_mfma_f32_16x16x32_bf16 v[2:5], v[170:173], v[202:205], v[2:5]
	v_mfma_f32_16x16x32_bf16 v[2:5], v[174:177], v[206:209], v[2:5]
	v_mfma_f32_16x16x32_bf16 v[6:9], v[166:169], v[206:209], v[6:9]
	v_mfma_f32_16x16x32_bf16 v[6:9], v[162:165], v[202:205], v[6:9]
	s_setprio 0
	s_barrier
	s_add_i32 s40, s40, 2
	s_add_u32 s26, s26, 0x100
	s_addc_u32 s27, s27, 0
	s_add_u32 s21, s21, 0x100
	s_addc_u32 s35, s35, 0
	s_cmp_gt_u32 s40, 29
	s_cbranch_scc0 .LBB0_359
	s_and_b64 vcc, exec, s[16:17]
	s_cbranch_vccz .LBB0_362
	s_barrier

; #define PG8_STAGE(bufoff, gbase, voff) do { _Pragma("unroll") for (int _i = 0; _i < 2; ++_i) \
;         __builtin_amdgcn_global_load_lds((const unsigned*)((const char*)(gbase) + (voff)[_i]), (LAS unsigned*)(lds + (bufoff) + ldsw + _i * 8192), 16, 0, 0); } while (0)
; #define PG8_LDA(dst, b, h) do { _Pragma("unroll") for (int m = 0; m < 4; ++m) _Pragma("unroll") for (int k = 0; k < 2; ++k) dst[m][k] = *(const LAS bf16x8*)(lds + PG8_SA(b, h) + aoff + m * 2048 + k * 1024); } while (0)
; #define PG8_LDB(dst, b, h) do { _Pragma("unroll") for (int n = 0; n < 2; ++n) _Pragma("unroll") for (int k = 0; k < 2; ++k) dst[n][k] = *(const LAS bf16x8*)(lds + PG8_SB(b, h) + boff + n * 2048 + k * 1024); } while (0)
; #define PG8_MMA(ai, bj, At, Bt) do { __builtin_amdgcn_s_setprio(1); _Pragma("unroll") for (int m = 0; m < 4; ++m) _Pragma("unroll") for (int n = 0; n < 2; ++n) _Pragma("unroll") for (int k = 0; k < 2; ++k) \
;         acc[ai][bj][m][n] = __builtin_amdgcn_mfma_f32_16x16x32_bf16(Bt[n][k], At[m][k], acc[ai][bj][m][n], 0, 0, 0); __builtin_amdgcn_s_setprio(0); } while (0)
; #define PG8_WAIT_V(n) asm volatile("s_waitcnt vmcnt(" #n ")" ::: "memory")
; #define PG8_WAIT_L(n) asm volatile("s_waitcnt lgkmcnt(" #n ")" ::: "memory")
; #define PG8_BAR __builtin_amdgcn_s_barrier()
; template <class Epi, class Sched, bool ALIGN_EPI = false, bool SP2 = false>
; __device__ __forceinline__ void gemm_phase(LAS unsigned char* lds, const Gemm g, const Sched& S, const Epi& E) {
;     ...
;             const bool last = (t == nt - 2);
;             const char* a1 = cA + (size_t)(t + 1) * kstep;
;             const char* a2 = last ? nA : cA + (size_t)(t + 2) * kstep; const char* b2 = last ? nB : cB + (size_t)(t + 2) * kstep;
;             const char* a3 = a2 + kstep; const char* b3 = b2 + kstep;
;             if (last && has_next) S.a_ready(nxt);
;             if constexpr (SP2) {
;             PG8_LDB(B0, 0, 0); PG8_LDB(B1, 0, 1); PG8_SCHED; PG8_LDA(At, 0, 0); PG8_STAGE(PG8_SA(1, 1), a1 + hstep, voffA);
;             PG8_WAIT_V(8); PG8_WAIT_L(0); PG8_BAR; PG8_MMA(0, 0, At, B0); PG8_MMA(0, 1, At, B1); PG8_BAR; PG8_SCHED;
;             PG8_LDA(At, 0, 1); PG8_STAGE(PG8_SB(0, 0), b2, voffB); PG8_STAGE(PG8_SB(0, 1), b2 + hstep, voffB); PG8_STAGE(PG8_SA(0, 0), a2, voffA);
;             PG8_WAIT_V(8); PG8_WAIT_L(0); PG8_BAR; PG8_MMA(1, 0, At, B0); PG8_MMA(1, 1, At, B1); PG8_BAR; PG8_SCHED;
.LBB0_833:
	s_add_u32 s28, s26, 0xfff80080
	s_addc_u32 s29, s27, -1
	s_add_i32 s53, 0, 0x10000
	s_cmp_eq_u32 s52, 28
	s_cselect_b32 s31, s21, s29
	s_cselect_b32 s30, s48, s28
	s_cselect_b32 s29, s19, s51
	s_cselect_b32 s28, s49, s50
	s_add_i32 s56, 0, 0x14000
	v_add_u32_e32 v134, s53, v247
	v_add_u32_e32 v158, s56, v247
	ds_read_b128 v[106:109], v134
	ds_read_b128 v[110:113], v134 offset:1024
	ds_read_b128 v[122:125], v134 offset:2048
	ds_read_b128 v[134:137], v134 offset:3072
	ds_read_b128 v[146:149], v158
	ds_read_b128 v[150:153], v158 offset:1024
	ds_read_b128 v[154:157], v158 offset:2048
	ds_read_b128 v[158:161], v158 offset:3072
	v_lshl_add_u64 v[204:205], s[26:27], 0, v[200:201]
	s_add_i32 m0, s8, 0xc000
	ds_read_b128 v[162:165], v249
	ds_read_b128 v[166:169], v249 offset:1024
	ds_read_b128 v[170:173], v249 offset:2048
	ds_read_b128 v[174:177], v249 offset:3072
	ds_read_b128 v[178:181], v249 offset:4096
	ds_read_b128 v[182:185], v249 offset:5120
	ds_read_b128 v[186:189], v249 offset:6144
	ds_read_b128 v[190:193], v249 offset:7168
	global_load_lds_dwordx4 v[204:205], off
	v_lshl_add_u64 v[204:205], s[26:27], 0, v[202:203]
	s_add_i32 m0, s8, 0xe000
	s_nop 0
	global_load_lds_dwordx4 v[204:205], off
	s_waitcnt vmcnt(8)
	s_waitcnt lgkmcnt(0)
	s_barrier
	s_setprio 1
	s_waitcnt lgkmcnt(0)
	v_mfma_f32_16x16x32_bf16 v[142:145], v[106:109], v[162:165], v[142:145]
	v_mfma_f32_16x16x32_bf16 v[142:145], v[110:113], v[166:169], v[142:145]
	v_mfma_f32_16x16x32_bf16 v[138:141], v[134:137], v[166:169], v[138:141]
	v_mfma_f32_16x16x32_bf16 v[138:141], v[122:125], v[162:165], v[138:141]
	v_mfma_f32_16x16x32_bf16 v[114:117], v[122:125], v[170:173], v[114:117]
	v_mfma_f32_16x16x32_bf16 v[114:117], v[134:137], v[174:177], v[114:117]
	v_mfma_f32_16x16x32_bf16 v[118:121], v[110:113], v[174:177], v[118:121]
	v_mfma_f32_16x16x32_bf16 v[118:121], v[106:109], v[170:173], v[118:121]
	v_mfma_f32_16x16x32_bf16 v[94:97], v[106:109], v[178:181], v[94:97]
	v_mfma_f32_16x16x32_bf16 v[94:97], v[110:113], v[182:185], v[94:97]
	v_mfma_f32_16x16x32_bf16 v[90:93], v[134:137], v[182:185], v[90:93]
	v_mfma_f32_16x16x32_bf16 v[90:93], v[122:125], v[178:181], v[90:93]
	v_mfma_f32_16x16x32_bf16 v[74:77], v[122:125], v[186:189], v[74:77]
	v_mfma_f32_16x16x32_bf16 v[74:77], v[134:137], v[190:193], v[74:77]
	v_mfma_f32_16x16x32_bf16 v[78:81], v[110:113], v[190:193], v[78:81]
	v_mfma_f32_16x16x32_bf16 v[78:81], v[106:109], v[186:189], v[78:81]
	s_setprio 0
	s_setprio 1
	v_mfma_f32_16x16x32_bf16 v[130:133], v[146:149], v[162:165], v[130:133]
	v_mfma_f32_16x16x32_bf16 v[130:133], v[150:153], v[166:169], v[130:133]
	v_mfma_f32_16x16x32_bf16 v[126:129], v[158:161], v[166:169], v[126:129]
	v_mfma_f32_16x16x32_bf16 v[126:129], v[154:157], v[162:165], v[126:129]
	v_mfma_f32_16x16x32_bf16 v[98:101], v[154:157], v[170:173], v[98:101]
	v_mfma_f32_16x16x32_bf16 v[98:101], v[158:161], v[174:177], v[98:101]
	v_mfma_f32_16x16x32_bf16 v[102:105], v[150:153], v[174:177], v[102:105]
	v_mfma_f32_16x16x32_bf16 v[102:105], v[146:149], v[170:173], v[102:105]
	v_mfma_f32_16x16x32_bf16 v[86:89], v[146:149], v[178:181], v[86:89]
	v_mfma_f32_16x16x32_bf16 v[86:89], v[150:153], v[182:185], v[86:89]
	v_mfma_f32_16x16x32_bf16 v[82:85], v[158:161], v[182:185], v[82:85]
	v_mfma_f32_16x16x32_bf16 v[82:85], v[154:157], v[178:181], v[82:85]
	v_mfma_f32_16x16x32_bf16 v[66:69], v[154:157], v[186:189], v[66:69]
	v_mfma_f32_16x16x32_bf16 v[66:69], v[158:161], v[190:193], v[66:69]
	v_mfma_f32_16x16x32_bf16 v[70:73], v[150:153], v[190:193], v[70:73]
	v_mfma_f32_16x16x32_bf16 v[70:73], v[146:149], v[186:189], v[70:73]
	s_setprio 0
	s_barrier
	s_add_i32 s53, s53, s7
	v_lshl_add_u64 v[204:205], s[28:29], 0, v[0:1]
	s_mov_b32 m0, s53
	ds_read_b128 v[162:165], v249 offset:16384
	ds_read_b128 v[166:169], v249 offset:17408
	ds_read_b128 v[170:173], v249 offset:18432
	ds_read_b128 v[174:177], v249 offset:19456
	ds_read_b128 v[178:181], v249 offset:20480
	ds_read_b128 v[182:185], v249 offset:21504
	ds_read_b128 v[186:189], v249 offset:22528
	ds_read_b128 v[190:193], v249 offset:23552
	global_load_lds_dwordx4 v[204:205], off
	s_add_i32 m0, s53, 0x2000
	s_add_u32 s54, s28, 0x80000
	v_lshl_add_u64 v[206:207], s[28:29], 0, v[194:195]
	s_addc_u32 s55, s29, 0
	s_add_i32 s53, s56, s7
	global_load_lds_dwordx4 v[206:207], off
	v_lshl_add_u64 v[208:209], s[54:55], 0, v[0:1]
	s_mov_b32 m0, s53
	v_lshl_add_u64 v[210:211], s[30:31], 0, v[196:197]
	global_load_lds_dwordx4 v[208:209], off
	v_lshl_add_u64 v[208:209], s[54:55], 0, v[194:195]
	s_add_i32 m0, s53, 0x2000
	s_nop 0
	global_load_lds_dwordx4 v[208:209], off
	v_lshl_add_u64 v[208:209], s[30:31], 0, v[198:199]
	s_mov_b32 m0, s8
	s_nop 0
	global_load_lds_dwordx4 v[208:209], off
	s_mov_b32 m0, s9
	s_nop 0
	global_load_lds_dwordx4 v[210:211], off
	s_waitcnt vmcnt(8)
	s_waitcnt lgkmcnt(0)
	s_barrier
; #define PG8_STAGE(bufoff, gbase, voff) do { _Pragma("unroll") for (int _i = 0; _i < 2; ++_i) \
;         __builtin_amdgcn_global_load_lds((const unsigned*)((const char*)(gbase) + (voff)[_i]), (LAS unsigned*)(lds + (bufoff) + ldsw + _i * 8192), 16, 0, 0); } while (0)
; #define PG8_LDA(dst, b, h) do { _Pragma("unroll") for (int m = 0; m < 4; ++m) _Pragma("unroll") for (int k = 0; k < 2; ++k) dst[m][k] = *(const LAS bf16x8*)(lds + PG8_SA(b, h) + aoff + m * 2048 + k * 1024); } while (0)
; #define PG8_LDB(dst, b, h) do { _Pragma("unroll") for (int n = 0; n < 2; ++n) _Pragma("unroll") for (int k = 0; k < 2; ++k) dst[n][k] = *(const LAS bf16x8*)(lds + PG8_SB(b, h) + boff + n * 2048 + k * 1024); } while (0)
; #define PG8_MMA(ai, bj, At, Bt) do { __builtin_amdgcn_s_setprio(1); _Pragma("unroll") for (int m = 0; m < 4; ++m) _Pragma("unroll") for (int n = 0; n < 2; ++n) _Pragma("unroll") for (int k = 0; k < 2; ++k) \
;         acc[ai][bj][m][n] = __builtin_amdgcn_mfma_f32_16x16x32_bf16(Bt[n][k], At[m][k], acc[ai][bj][m][n], 0, 0, 0); __builtin_amdgcn_s_setprio(0); } while (0)
; #define PG8_WAIT_V(n) asm volatile("s_waitcnt vmcnt(" #n ")" ::: "memory")
; #define PG8_WAIT_L(n) asm volatile("s_waitcnt lgkmcnt(" #n ")" ::: "memory")
; #define PG8_BAR __builtin_amdgcn_s_barrier()
; #define PG8_SCHED __builtin_amdgcn_sched_barrier(0)
; template <class Epi, class Sched, bool ALIGN_EPI = false, bool SP2 = false>
; __device__ __forceinline__ void gemm_phase(LAS unsigned char* lds, const Gemm g, const Sched& S, const Epi& E) {
;     ...
;             PG8_WAIT_V(8); PG8_WAIT_L(0); PG8_BAR; PG8_MMA(1, 0, At, B0); PG8_MMA(1, 1, At, B1); PG8_BAR; PG8_SCHED;
;             PG8_LDB(B0, 1, 0); PG8_LDB(B1, 1, 1); PG8_SCHED; PG8_LDA(At, 1, 0); PG8_STAGE(PG8_SA(0, 1), a2 + hstep, voffA);
;             PG8_WAIT_V(8); PG8_WAIT_L(0); PG8_BAR; PG8_MMA(0, 0, At, B0); PG8_MMA(0, 1, At, B1); PG8_BAR; PG8_SCHED;
	s_setprio 1
	s_waitcnt lgkmcnt(0)
	v_mfma_f32_16x16x32_bf16 v[62:65], v[106:109], v[162:165], v[62:65]
	v_mfma_f32_16x16x32_bf16 v[62:65], v[110:113], v[166:169], v[62:65]
	v_mfma_f32_16x16x32_bf16 v[58:61], v[134:137], v[166:169], v[58:61]
	v_mfma_f32_16x16x32_bf16 v[58:61], v[122:125], v[162:165], v[58:61]
	v_mfma_f32_16x16x32_bf16 v[42:45], v[122:125], v[170:173], v[42:45]
	v_mfma_f32_16x16x32_bf16 v[42:45], v[134:137], v[174:177], v[42:45]
	v_mfma_f32_16x16x32_bf16 v[46:49], v[110:113], v[174:177], v[46:49]
	v_mfma_f32_16x16x32_bf16 v[46:49], v[106:109], v[170:173], v[46:49]
	v_mfma_f32_16x16x32_bf16 v[30:33], v[106:109], v[178:181], v[30:33]
	v_mfma_f32_16x16x32_bf16 v[30:33], v[110:113], v[182:185], v[30:33]
	v_mfma_f32_16x16x32_bf16 v[26:29], v[134:137], v[182:185], v[26:29]
	v_mfma_f32_16x16x32_bf16 v[26:29], v[122:125], v[178:181], v[26:29]
	v_mfma_f32_16x16x32_bf16 v[10:13], v[122:125], v[186:189], v[10:13]
	v_mfma_f32_16x16x32_bf16 v[10:13], v[134:137], v[190:193], v[10:13]
	v_mfma_f32_16x16x32_bf16 v[14:17], v[110:113], v[190:193], v[14:17]
	v_mfma_f32_16x16x32_bf16 v[14:17], v[106:109], v[186:189], v[14:17]
	s_setprio 0
	s_setprio 1
	v_mfma_f32_16x16x32_bf16 v[54:57], v[146:149], v[162:165], v[54:57]
	v_mfma_f32_16x16x32_bf16 v[54:57], v[150:153], v[166:169], v[54:57]
	v_mfma_f32_16x16x32_bf16 v[50:53], v[158:161], v[166:169], v[50:53]
	v_mfma_f32_16x16x32_bf16 v[50:53], v[154:157], v[162:165], v[50:53]
	v_mfma_f32_16x16x32_bf16 v[34:37], v[154:157], v[170:173], v[34:37]
	v_mfma_f32_16x16x32_bf16 v[34:37], v[158:161], v[174:177], v[34:37]
	v_mfma_f32_16x16x32_bf16 v[38:41], v[150:153], v[174:177], v[38:41]
	v_mfma_f32_16x16x32_bf16 v[38:41], v[146:149], v[170:173], v[38:41]
	v_mfma_f32_16x16x32_bf16 v[22:25], v[146:149], v[178:181], v[22:25]
	v_mfma_f32_16x16x32_bf16 v[22:25], v[150:153], v[182:185], v[22:25]
	v_mfma_f32_16x16x32_bf16 v[18:21], v[158:161], v[182:185], v[18:21]
	v_mfma_f32_16x16x32_bf16 v[18:21], v[154:157], v[178:181], v[18:21]
	v_mfma_f32_16x16x32_bf16 v[2:5], v[154:157], v[186:189], v[2:5]
	v_mfma_f32_16x16x32_bf16 v[2:5], v[158:161], v[190:193], v[2:5]
	v_mfma_f32_16x16x32_bf16 v[6:9], v[150:153], v[190:193], v[6:9]
	v_mfma_f32_16x16x32_bf16 v[6:9], v[146:149], v[186:189], v[6:9]
	s_setprio 0
	s_barrier
	s_add_i32 s53, 0, 0x18000
	s_add_i32 s54, 0, 0x1c000
	v_add_u32_e32 v134, s53, v247
	v_add_u32_e32 v158, s54, v247
	ds_read_b128 v[106:109], v134
	ds_read_b128 v[110:113], v134 offset:1024
	ds_read_b128 v[122:125], v134 offset:2048
	ds_read_b128 v[134:137], v134 offset:3072
	ds_read_b128 v[146:149], v158
	ds_read_b128 v[150:153], v158 offset:1024
	ds_read_b128 v[154:157], v158 offset:2048
	ds_read_b128 v[158:161], v158 offset:3072
	s_add_u32 s30, s30, 0x80000
	s_addc_u32 s31, s31, 0
	s_mov_b32 m0, s35
	v_lshl_add_u64 v[212:213], s[30:31], 0, v[198:199]
	ds_read_b128 v[162:165], v249 offset:32768
	ds_read_b128 v[166:169], v249 offset:33792
	ds_read_b128 v[170:173], v249 offset:34816
	ds_read_b128 v[174:177], v249 offset:35840
	ds_read_b128 v[178:181], v249 offset:36864
	ds_read_b128 v[182:185], v249 offset:37888
	ds_read_b128 v[186:189], v249 offset:38912
	ds_read_b128 v[190:193], v249 offset:39936
	global_load_lds_dwordx4 v[212:213], off
	v_lshl_add_u64 v[212:213], s[30:31], 0, v[196:197]
	s_mov_b32 m0, s42
	s_nop 0
	global_load_lds_dwordx4 v[212:213], off
	s_waitcnt vmcnt(8)
	s_waitcnt lgkmcnt(0)
	s_barrier
	s_setprio 1
	s_waitcnt lgkmcnt(0)
	v_mfma_f32_16x16x32_bf16 v[142:145], v[106:109], v[162:165], v[142:145]
	v_mfma_f32_16x16x32_bf16 v[142:145], v[110:113], v[166:169], v[142:145]
	v_mfma_f32_16x16x32_bf16 v[138:141], v[134:137], v[166:169], v[138:141]
	v_mfma_f32_16x16x32_bf16 v[138:141], v[122:125], v[162:165], v[138:141]
	v_mfma_f32_16x16x32_bf16 v[114:117], v[122:125], v[170:173], v[114:117]
	v_mfma_f32_16x16x32_bf16 v[114:117], v[134:137], v[174:177], v[114:117]
	v_mfma_f32_16x16x32_bf16 v[118:121], v[110:113], v[174:177], v[118:121]
	v_mfma_f32_16x16x32_bf16 v[118:121], v[106:109], v[170:173], v[118:121]
	v_mfma_f32_16x16x32_bf16 v[94:97], v[106:109], v[178:181], v[94:97]
	v_mfma_f32_16x16x32_bf16 v[94:97], v[110:113], v[182:185], v[94:97]
	v_mfma_f32_16x16x32_bf16 v[90:93], v[134:137], v[182:185], v[90:93]
	v_mfma_f32_16x16x32_bf16 v[90:93], v[122:125], v[178:181], v[90:93]
	v_mfma_f32_16x16x32_bf16 v[74:77], v[122:125], v[186:189], v[74:77]
	v_mfma_f32_16x16x32_bf16 v[74:77], v[134:137], v[190:193], v[74:77]
	v_mfma_f32_16x16x32_bf16 v[78:81], v[110:113], v[190:193], v[78:81]
	v_mfma_f32_16x16x32_bf16 v[78:81], v[106:109], v[186:189], v[78:81]
	s_setprio 0
	s_setprio 1
	v_mfma_f32_16x16x32_bf16 v[130:133], v[146:149], v[162:165], v[130:133]
	v_mfma_f32_16x16x32_bf16 v[130:133], v[150:153], v[166:169], v[130:133]
	v_mfma_f32_16x16x32_bf16 v[126:129], v[158:161], v[166:169], v[126:129]
	v_mfma_f32_16x16x32_bf16 v[126:129], v[154:157], v[162:165], v[126:129]
	v_mfma_f32_16x16x32_bf16 v[98:101], v[154:157], v[170:173], v[98:101]
	v_mfma_f32_16x16x32_bf16 v[98:101], v[158:161], v[174:177], v[98:101]
	v_mfma_f32_16x16x32_bf16 v[102:105], v[150:153], v[174:177], v[102:105]
	v_mfma_f32_16x16x32_bf16 v[102:105], v[146:149], v[170:173], v[102:105]
	v_mfma_f32_16x16x32_bf16 v[86:89], v[146:149], v[178:181], v[86:89]
	v_mfma_f32_16x16x32_bf16 v[86:89], v[150:153], v[182:185], v[86:89]
	v_mfma_f32_16x16x32_bf16 v[82:85], v[158:161], v[182:185], v[82:85]
	v_mfma_f32_16x16x32_bf16 v[82:85], v[154:157], v[178:181], v[82:85]
	v_mfma_f32_16x16x32_bf16 v[66:69], v[154:157], v[186:189], v[66:69]
	v_mfma_f32_16x16x32_bf16 v[66:69], v[158:161], v[190:193], v[66:69]
	v_mfma_f32_16x16x32_bf16 v[70:73], v[150:153], v[190:193], v[70:73]
	v_mfma_f32_16x16x32_bf16 v[70:73], v[146:149], v[186:189], v[70:73]
	s_setprio 0
	s_barrier
; #define PG8_STAGE(bufoff, gbase, voff) do { _Pragma("unroll") for (int _i = 0; _i < 2; ++_i) \
;         __builtin_amdgcn_global_load_lds((const unsigned*)((const char*)(gbase) + (voff)[_i]), (LAS unsigned*)(lds + (bufoff) + ldsw + _i * 8192), 16, 0, 0); } while (0)
; #define PG8_LDA(dst, b, h) do { _Pragma("unroll") for (int m = 0; m < 4; ++m) _Pragma("unroll") for (int k = 0; k < 2; ++k) dst[m][k] = *(const LAS bf16x8*)(lds + PG8_SA(b, h) + aoff + m * 2048 + k * 1024); } while (0)
; #define PG8_MMA(ai, bj, At, Bt) do { __builtin_amdgcn_s_setprio(1); _Pragma("unroll") for (int m = 0; m < 4; ++m) _Pragma("unroll") for (int n = 0; n < 2; ++n) _Pragma("unroll") for (int k = 0; k < 2; ++k) \
;         acc[ai][bj][m][n] = __builtin_amdgcn_mfma_f32_16x16x32_bf16(Bt[n][k], At[m][k], acc[ai][bj][m][n], 0, 0, 0); __builtin_amdgcn_s_setprio(0); } while (0)
; #define PG8_WAIT_V(n) asm volatile("s_waitcnt vmcnt(" #n ")" ::: "memory")
; #define PG8_WAIT_L(n) asm volatile("s_waitcnt lgkmcnt(" #n ")" ::: "memory")
; #define PG8_BAR __builtin_amdgcn_s_barrier()
; #define PG8_SCHED __builtin_amdgcn_sched_barrier(0)
; template <class Epi, class Sched, bool ALIGN_EPI = false, bool SP2 = false>
; __device__ __forceinline__ void gemm_phase(LAS unsigned char* lds, const Gemm g, const Sched& S, const Epi& E) {
;     ...
;             PG8_LDA(At, 1, 1); PG8_STAGE(PG8_SB(1, 0), b3, voffB); PG8_STAGE(PG8_SB(1, 1), b3 + hstep, voffB); PG8_STAGE(PG8_SA(1, 0), a3, voffA);
;             PG8_WAIT_V(8); PG8_WAIT_L(0); PG8_BAR; PG8_MMA(1, 0, At, B0); PG8_MMA(1, 1, At, B1); PG8_BAR; PG8_SCHED;
;     ...
;         if constexpr (ALIGN_EPI) { if (wr == 0) PG8_BAR; }
	s_add_i32 s30, s53, s7
	v_lshl_add_u64 v[204:205], v[204:205], 0, s[12:13]
	s_mov_b32 m0, s30
	ds_read_b128 v[162:165], v249 offset:49152
	ds_read_b128 v[166:169], v249 offset:50176
	ds_read_b128 v[170:173], v249 offset:51200
	ds_read_b128 v[174:177], v249 offset:52224
	ds_read_b128 v[178:181], v249 offset:53248
	ds_read_b128 v[182:185], v249 offset:54272
	ds_read_b128 v[186:189], v249 offset:55296
	ds_read_b128 v[190:193], v249 offset:56320
	global_load_lds_dwordx4 v[204:205], off
	s_add_i32 m0, s30, 0x2000
	s_add_u32 s28, s28, 0x80080
	v_lshl_add_u64 v[204:205], v[206:207], 0, s[12:13]
	s_addc_u32 s29, s29, 0
	s_add_i32 s30, s54, s7
	global_load_lds_dwordx4 v[204:205], off
	v_lshl_add_u64 v[204:205], s[28:29], 0, v[0:1]
	s_mov_b32 m0, s30
	s_nop 0
	global_load_lds_dwordx4 v[204:205], off
	v_lshl_add_u64 v[204:205], s[28:29], 0, v[194:195]
	s_add_i32 m0, s30, 0x2000
	s_nop 0
	global_load_lds_dwordx4 v[204:205], off
	v_lshl_add_u64 v[204:205], v[208:209], 0, s[12:13]
	s_mov_b32 m0, s43
	s_nop 0
	global_load_lds_dwordx4 v[204:205], off
	v_lshl_add_u64 v[204:205], v[210:211], 0, s[12:13]
	s_mov_b32 m0, s44
	s_nop 0
	global_load_lds_dwordx4 v[204:205], off
	s_waitcnt vmcnt(8)
	s_waitcnt lgkmcnt(0)
	s_barrier
	s_setprio 1
	s_waitcnt lgkmcnt(0)
	v_mfma_f32_16x16x32_bf16 v[62:65], v[106:109], v[162:165], v[62:65]
	v_mfma_f32_16x16x32_bf16 v[62:65], v[110:113], v[166:169], v[62:65]
	v_mfma_f32_16x16x32_bf16 v[58:61], v[134:137], v[166:169], v[58:61]
	v_mfma_f32_16x16x32_bf16 v[58:61], v[122:125], v[162:165], v[58:61]
	v_mfma_f32_16x16x32_bf16 v[42:45], v[122:125], v[170:173], v[42:45]
	v_mfma_f32_16x16x32_bf16 v[42:45], v[134:137], v[174:177], v[42:45]
	v_mfma_f32_16x16x32_bf16 v[46:49], v[110:113], v[174:177], v[46:49]
	v_mfma_f32_16x16x32_bf16 v[46:49], v[106:109], v[170:173], v[46:49]
	v_mfma_f32_16x16x32_bf16 v[30:33], v[106:109], v[178:181], v[30:33]
	v_mfma_f32_16x16x32_bf16 v[30:33], v[110:113], v[182:185], v[30:33]
	v_mfma_f32_16x16x32_bf16 v[26:29], v[134:137], v[182:185], v[26:29]
	v_mfma_f32_16x16x32_bf16 v[26:29], v[122:125], v[178:181], v[26:29]
	v_mfma_f32_16x16x32_bf16 v[10:13], v[122:125], v[186:189], v[10:13]
	v_mfma_f32_16x16x32_bf16 v[10:13], v[134:137], v[190:193], v[10:13]
	v_mfma_f32_16x16x32_bf16 v[14:17], v[110:113], v[190:193], v[14:17]
	v_mfma_f32_16x16x32_bf16 v[14:17], v[106:109], v[186:189], v[14:17]
	s_setprio 0
	s_setprio 1
	v_mfma_f32_16x16x32_bf16 v[54:57], v[146:149], v[162:165], v[54:57]
	v_mfma_f32_16x16x32_bf16 v[54:57], v[150:153], v[166:169], v[54:57]
	v_mfma_f32_16x16x32_bf16 v[50:53], v[158:161], v[166:169], v[50:53]
	v_mfma_f32_16x16x32_bf16 v[50:53], v[154:157], v[162:165], v[50:53]
	v_mfma_f32_16x16x32_bf16 v[34:37], v[154:157], v[170:173], v[34:37]
	v_mfma_f32_16x16x32_bf16 v[34:37], v[158:161], v[174:177], v[34:37]
	v_mfma_f32_16x16x32_bf16 v[38:41], v[150:153], v[174:177], v[38:41]
	v_mfma_f32_16x16x32_bf16 v[38:41], v[146:149], v[170:173], v[38:41]
	v_mfma_f32_16x16x32_bf16 v[22:25], v[146:149], v[178:181], v[22:25]
	v_mfma_f32_16x16x32_bf16 v[22:25], v[150:153], v[182:185], v[22:25]
	v_mfma_f32_16x16x32_bf16 v[18:21], v[158:161], v[182:185], v[18:21]
	v_mfma_f32_16x16x32_bf16 v[18:21], v[154:157], v[178:181], v[18:21]
	v_mfma_f32_16x16x32_bf16 v[2:5], v[154:157], v[186:189], v[2:5]
	v_mfma_f32_16x16x32_bf16 v[2:5], v[158:161], v[190:193], v[2:5]
	v_mfma_f32_16x16x32_bf16 v[6:9], v[150:153], v[190:193], v[6:9]
	v_mfma_f32_16x16x32_bf16 v[6:9], v[146:149], v[186:189], v[6:9]
	s_setprio 0
	s_barrier
	s_add_i32 s52, s52, 2
	s_add_u32 s26, s26, 0x100
	s_addc_u32 s27, s27, 0
	s_add_u32 s50, s50, 0x100
	s_addc_u32 s51, s51, 0
	s_cmp_gt_u32 s52, 29
	s_cbranch_scc0 .LBB0_833
	s_and_b64 vcc, exec, s[16:17]
	s_cbranch_vccz .LBB0_836
	s_barrier

; #define PG8_STAGE(bufoff, gbase, voff) do { _Pragma("unroll") for (int _i = 0; _i < 2; ++_i) \
;         __builtin_amdgcn_global_load_lds((const unsigned*)((const char*)(gbase) + (voff)[_i]), (LAS unsigned*)(lds + (bufoff) + ldsw + _i * 8192), 16, 0, 0); } while (0)
; #define PG8_LDA(dst, b, h) do { _Pragma("unroll") for (int m = 0; m < 4; ++m) _Pragma("unroll") for (int k = 0; k < 2; ++k) dst[m][k] = *(const LAS bf16x8*)(lds + PG8_SA(b, h) + aoff + m * 2048 + k * 1024); } while (0)
; #define PG8_LDB(dst, b, h) do { _Pragma("unroll") for (int n = 0; n < 2; ++n) _Pragma("unroll") for (int k = 0; k < 2; ++k) dst[n][k] = *(const LAS bf16x8*)(lds + PG8_SB(b, h) + boff + n * 2048 + k * 1024); } while (0)
; #define PG8_MMA(ai, bj, At, Bt) do { __builtin_amdgcn_s_setprio(1); _Pragma("unroll") for (int m = 0; m < 4; ++m) _Pragma("unroll") for (int n = 0; n < 2; ++n) _Pragma("unroll") for (int k = 0; k < 2; ++k) \
;         acc[ai][bj][m][n] = __builtin_amdgcn_mfma_f32_16x16x32_bf16(Bt[n][k], At[m][k], acc[ai][bj][m][n], 0, 0, 0); __builtin_amdgcn_s_setprio(0); } while (0)
; #define PG8_WAIT_V(n) asm volatile("s_waitcnt vmcnt(" #n ")" ::: "memory")
; #define PG8_WAIT_L(n) asm volatile("s_waitcnt lgkmcnt(" #n ")" ::: "memory")
; #define PG8_BAR __builtin_amdgcn_s_barrier()
; template <class Epi, class Sched, bool ALIGN_EPI = false, bool SP2 = false>
; __device__ __forceinline__ void gemm_phase(LAS unsigned char* lds, const Gemm g, const Sched& S, const Epi& E) {
;     ...
;             const bool last = (t == nt - 2);
;             const char* a1 = cA + (size_t)(t + 1) * kstep;
;             const char* a2 = last ? nA : cA + (size_t)(t + 2) * kstep; const char* b2 = last ? nB : cB + (size_t)(t + 2) * kstep;
;             const char* a3 = a2 + kstep; const char* b3 = b2 + kstep;
;             if (last && has_next) S.a_ready(nxt);
;             if constexpr (SP2) {
;             PG8_LDB(B0, 0, 0); PG8_LDB(B1, 0, 1); PG8_SCHED; PG8_LDA(At, 0, 0); PG8_STAGE(PG8_SA(1, 1), a1 + hstep, voffA);
;             PG8_WAIT_V(8); PG8_WAIT_L(0); PG8_BAR; PG8_MMA(0, 0, At, B0); PG8_MMA(0, 1, At, B1); PG8_BAR; PG8_SCHED;
;             PG8_LDA(At, 0, 1); PG8_STAGE(PG8_SB(0, 0), b2, voffB); PG8_STAGE(PG8_SB(0, 1), b2 + hstep, voffB); PG8_STAGE(PG8_SA(0, 0), a2, voffA);
;             PG8_WAIT_V(8); PG8_WAIT_L(0); PG8_BAR; PG8_MMA(1, 0, At, B0); PG8_MMA(1, 1, At, B1); PG8_BAR; PG8_SCHED;
.LBB0_924:
	s_add_u32 s28, s26, 0xfff80080
	s_addc_u32 s29, s27, -1
	s_add_i32 s51, 0, 0x10000
	s_cmp_eq_u32 s50, 28
	s_cselect_b32 s31, s7, s29
	s_cselect_b32 s30, s8, s28
	v_add_u32_e32 v148, s51, v151
	s_cselect_b32 s29, s19, s49
	s_cselect_b32 s28, s21, s35
	s_add_i32 s54, 0, 0x14000
	ds_read_b128 v[140:143], v148
	ds_read_b128 v[144:147], v148 offset:1024
	ds_read_b128 v[156:159], v148 offset:2048
	ds_read_b128 v[160:163], v148 offset:3072
	v_add_u32_e32 v148, s54, v151
	ds_read_b128 v[164:167], v148
	ds_read_b128 v[168:171], v148 offset:1024
	ds_read_b128 v[172:175], v148 offset:2048
	ds_read_b128 v[176:179], v148 offset:3072
	v_lshl_add_u64 v[212:213], s[26:27], 0, v[136:137]
	s_add_i32 m0, s42, 0xc000
	ds_read_b128 v[180:183], v155
	ds_read_b128 v[184:187], v155 offset:1024
	ds_read_b128 v[188:191], v155 offset:2048
	ds_read_b128 v[192:195], v155 offset:3072
	ds_read_b128 v[196:199], v155 offset:4096
	ds_read_b128 v[200:203], v155 offset:5120
	ds_read_b128 v[204:207], v155 offset:6144
	ds_read_b128 v[208:211], v155 offset:7168
	global_load_lds_dwordx4 v[212:213], off
	v_lshl_add_u64 v[212:213], s[26:27], 0, v[138:139]
	s_add_i32 m0, s42, 0xe000
	s_nop 0
	global_load_lds_dwordx4 v[212:213], off
	s_waitcnt vmcnt(8)
	s_waitcnt lgkmcnt(0)
	s_barrier
	s_setprio 1
	s_waitcnt lgkmcnt(0)
	v_mfma_f32_16x16x32_bf16 v[126:129], v[140:143], v[180:183], v[126:129]
	v_mfma_f32_16x16x32_bf16 v[126:129], v[144:147], v[184:187], v[126:129]
	v_mfma_f32_16x16x32_bf16 v[122:125], v[160:163], v[184:187], v[122:125]
	v_mfma_f32_16x16x32_bf16 v[122:125], v[156:159], v[180:183], v[122:125]
	v_mfma_f32_16x16x32_bf16 v[106:109], v[156:159], v[188:191], v[106:109]
	v_mfma_f32_16x16x32_bf16 v[106:109], v[160:163], v[192:195], v[106:109]
	v_mfma_f32_16x16x32_bf16 v[110:113], v[144:147], v[192:195], v[110:113]
	v_mfma_f32_16x16x32_bf16 v[110:113], v[140:143], v[188:191], v[110:113]
	v_mfma_f32_16x16x32_bf16 v[94:97], v[140:143], v[196:199], v[94:97]
	v_mfma_f32_16x16x32_bf16 v[94:97], v[144:147], v[200:203], v[94:97]
	v_mfma_f32_16x16x32_bf16 v[90:93], v[160:163], v[200:203], v[90:93]
	v_mfma_f32_16x16x32_bf16 v[90:93], v[156:159], v[196:199], v[90:93]
	v_mfma_f32_16x16x32_bf16 v[74:77], v[156:159], v[204:207], v[74:77]
	v_mfma_f32_16x16x32_bf16 v[74:77], v[160:163], v[208:211], v[74:77]
	v_mfma_f32_16x16x32_bf16 v[78:81], v[144:147], v[208:211], v[78:81]
	v_mfma_f32_16x16x32_bf16 v[78:81], v[140:143], v[204:207], v[78:81]
	s_setprio 0
	s_setprio 1
	v_mfma_f32_16x16x32_bf16 v[118:121], v[164:167], v[180:183], v[118:121]
	v_mfma_f32_16x16x32_bf16 v[118:121], v[168:171], v[184:187], v[118:121]
	v_mfma_f32_16x16x32_bf16 v[114:117], v[176:179], v[184:187], v[114:117]
	v_mfma_f32_16x16x32_bf16 v[114:117], v[172:175], v[180:183], v[114:117]
	v_mfma_f32_16x16x32_bf16 v[98:101], v[172:175], v[188:191], v[98:101]
	v_mfma_f32_16x16x32_bf16 v[98:101], v[176:179], v[192:195], v[98:101]
	v_mfma_f32_16x16x32_bf16 v[102:105], v[168:171], v[192:195], v[102:105]
	v_mfma_f32_16x16x32_bf16 v[102:105], v[164:167], v[188:191], v[102:105]
	v_mfma_f32_16x16x32_bf16 v[86:89], v[164:167], v[196:199], v[86:89]
	v_mfma_f32_16x16x32_bf16 v[86:89], v[168:171], v[200:203], v[86:89]
	v_mfma_f32_16x16x32_bf16 v[82:85], v[176:179], v[200:203], v[82:85]
	v_mfma_f32_16x16x32_bf16 v[82:85], v[172:175], v[196:199], v[82:85]
	v_mfma_f32_16x16x32_bf16 v[66:69], v[172:175], v[204:207], v[66:69]
	v_mfma_f32_16x16x32_bf16 v[66:69], v[176:179], v[208:211], v[66:69]
	v_mfma_f32_16x16x32_bf16 v[70:73], v[168:171], v[208:211], v[70:73]
	v_mfma_f32_16x16x32_bf16 v[70:73], v[164:167], v[204:207], v[70:73]
	s_setprio 0
	s_barrier
	s_add_i32 s51, s51, s41
	v_lshl_add_u64 v[212:213], s[28:29], 0, v[0:1]
	s_mov_b32 m0, s51
	ds_read_b128 v[180:183], v155 offset:16384
	ds_read_b128 v[184:187], v155 offset:17408
	ds_read_b128 v[188:191], v155 offset:18432
	ds_read_b128 v[192:195], v155 offset:19456
	ds_read_b128 v[196:199], v155 offset:20480
	ds_read_b128 v[200:203], v155 offset:21504
	ds_read_b128 v[204:207], v155 offset:22528
	ds_read_b128 v[208:211], v155 offset:23552
	global_load_lds_dwordx4 v[212:213], off
	s_add_i32 m0, s51, 0x2000
	s_add_u32 s52, s28, 0x80000
	v_lshl_add_u64 v[214:215], s[28:29], 0, v[130:131]
	s_addc_u32 s53, s29, 0
	s_add_i32 s51, s54, s41
	global_load_lds_dwordx4 v[214:215], off
	v_lshl_add_u64 v[216:217], s[52:53], 0, v[0:1]
	s_mov_b32 m0, s51
	v_lshl_add_u64 v[218:219], s[30:31], 0, v[132:133]
	global_load_lds_dwordx4 v[216:217], off
	v_lshl_add_u64 v[216:217], s[52:53], 0, v[130:131]
	s_add_i32 m0, s51, 0x2000
	s_nop 0
	global_load_lds_dwordx4 v[216:217], off
	v_lshl_add_u64 v[216:217], s[30:31], 0, v[134:135]
	s_mov_b32 m0, s42
	s_nop 0
	global_load_lds_dwordx4 v[216:217], off
	s_mov_b32 m0, s43
	s_nop 0
	global_load_lds_dwordx4 v[218:219], off
	s_waitcnt vmcnt(8)
	s_waitcnt lgkmcnt(0)
	s_barrier
; #define PG8_STAGE(bufoff, gbase, voff) do { _Pragma("unroll") for (int _i = 0; _i < 2; ++_i) \
;         __builtin_amdgcn_global_load_lds((const unsigned*)((const char*)(gbase) + (voff)[_i]), (LAS unsigned*)(lds + (bufoff) + ldsw + _i * 8192), 16, 0, 0); } while (0)
; #define PG8_LDA(dst, b, h) do { _Pragma("unroll") for (int m = 0; m < 4; ++m) _Pragma("unroll") for (int k = 0; k < 2; ++k) dst[m][k] = *(const LAS bf16x8*)(lds + PG8_SA(b, h) + aoff + m * 2048 + k * 1024); } while (0)
; #define PG8_LDB(dst, b, h) do { _Pragma("unroll") for (int n = 0; n < 2; ++n) _Pragma("unroll") for (int k = 0; k < 2; ++k) dst[n][k] = *(const LAS bf16x8*)(lds + PG8_SB(b, h) + boff + n * 2048 + k * 1024); } while (0)
; #define PG8_MMA(ai, bj, At, Bt) do { __builtin_amdgcn_s_setprio(1); _Pragma("unroll") for (int m = 0; m < 4; ++m) _Pragma("unroll") for (int n = 0; n < 2; ++n) _Pragma("unroll") for (int k = 0; k < 2; ++k) \
;         acc[ai][bj][m][n] = __builtin_amdgcn_mfma_f32_16x16x32_bf16(Bt[n][k], At[m][k], acc[ai][bj][m][n], 0, 0, 0); __builtin_amdgcn_s_setprio(0); } while (0)
; #define PG8_WAIT_V(n) asm volatile("s_waitcnt vmcnt(" #n ")" ::: "memory")
; #define PG8_WAIT_L(n) asm volatile("s_waitcnt lgkmcnt(" #n ")" ::: "memory")
; #define PG8_BAR __builtin_amdgcn_s_barrier()
; #define PG8_SCHED __builtin_amdgcn_sched_barrier(0)
; template <class Epi, class Sched, bool ALIGN_EPI = false, bool SP2 = false>
; __device__ __forceinline__ void gemm_phase(LAS unsigned char* lds, const Gemm g, const Sched& S, const Epi& E) {
;     ...
;             PG8_WAIT_V(8); PG8_WAIT_L(0); PG8_BAR; PG8_MMA(1, 0, At, B0); PG8_MMA(1, 1, At, B1); PG8_BAR; PG8_SCHED;
;             PG8_LDB(B0, 1, 0); PG8_LDB(B1, 1, 1); PG8_SCHED; PG8_LDA(At, 1, 0); PG8_STAGE(PG8_SA(0, 1), a2 + hstep, voffA);
;             PG8_WAIT_V(8); PG8_WAIT_L(0); PG8_BAR; PG8_MMA(0, 0, At, B0); PG8_MMA(0, 1, At, B1); PG8_BAR; PG8_SCHED;
	s_setprio 1
	s_waitcnt lgkmcnt(0)
	v_mfma_f32_16x16x32_bf16 v[62:65], v[140:143], v[180:183], v[62:65]
	v_mfma_f32_16x16x32_bf16 v[62:65], v[144:147], v[184:187], v[62:65]
	v_mfma_f32_16x16x32_bf16 v[58:61], v[160:163], v[184:187], v[58:61]
	v_mfma_f32_16x16x32_bf16 v[58:61], v[156:159], v[180:183], v[58:61]
	v_mfma_f32_16x16x32_bf16 v[42:45], v[156:159], v[188:191], v[42:45]
	v_mfma_f32_16x16x32_bf16 v[42:45], v[160:163], v[192:195], v[42:45]
	v_mfma_f32_16x16x32_bf16 v[46:49], v[144:147], v[192:195], v[46:49]
	v_mfma_f32_16x16x32_bf16 v[46:49], v[140:143], v[188:191], v[46:49]
	v_mfma_f32_16x16x32_bf16 v[30:33], v[140:143], v[196:199], v[30:33]
	v_mfma_f32_16x16x32_bf16 v[30:33], v[144:147], v[200:203], v[30:33]
	v_mfma_f32_16x16x32_bf16 v[26:29], v[160:163], v[200:203], v[26:29]
	v_mfma_f32_16x16x32_bf16 v[26:29], v[156:159], v[196:199], v[26:29]
	v_mfma_f32_16x16x32_bf16 v[10:13], v[156:159], v[204:207], v[10:13]
	v_mfma_f32_16x16x32_bf16 v[10:13], v[160:163], v[208:211], v[10:13]
	v_mfma_f32_16x16x32_bf16 v[14:17], v[144:147], v[208:211], v[14:17]
	v_mfma_f32_16x16x32_bf16 v[14:17], v[140:143], v[204:207], v[14:17]
	s_setprio 0
	s_setprio 1
	v_mfma_f32_16x16x32_bf16 v[54:57], v[164:167], v[180:183], v[54:57]
	v_mfma_f32_16x16x32_bf16 v[54:57], v[168:171], v[184:187], v[54:57]
	v_mfma_f32_16x16x32_bf16 v[50:53], v[176:179], v[184:187], v[50:53]
	v_mfma_f32_16x16x32_bf16 v[50:53], v[172:175], v[180:183], v[50:53]
	v_mfma_f32_16x16x32_bf16 v[34:37], v[172:175], v[188:191], v[34:37]
	v_mfma_f32_16x16x32_bf16 v[34:37], v[176:179], v[192:195], v[34:37]
	v_mfma_f32_16x16x32_bf16 v[38:41], v[168:171], v[192:195], v[38:41]
	v_mfma_f32_16x16x32_bf16 v[38:41], v[164:167], v[188:191], v[38:41]
	v_mfma_f32_16x16x32_bf16 v[22:25], v[164:167], v[196:199], v[22:25]
	v_mfma_f32_16x16x32_bf16 v[22:25], v[168:171], v[200:203], v[22:25]
	v_mfma_f32_16x16x32_bf16 v[18:21], v[176:179], v[200:203], v[18:21]
	v_mfma_f32_16x16x32_bf16 v[18:21], v[172:175], v[196:199], v[18:21]
	v_mfma_f32_16x16x32_bf16 v[2:5], v[172:175], v[204:207], v[2:5]
	v_mfma_f32_16x16x32_bf16 v[2:5], v[176:179], v[208:211], v[2:5]
	v_mfma_f32_16x16x32_bf16 v[6:9], v[168:171], v[208:211], v[6:9]
	v_mfma_f32_16x16x32_bf16 v[6:9], v[164:167], v[204:207], v[6:9]
	s_setprio 0
	s_barrier
	s_add_i32 s51, 0, 0x18000
	v_add_u32_e32 v148, s51, v151
	s_add_i32 s52, 0, 0x1c000
	ds_read_b128 v[140:143], v148
	ds_read_b128 v[144:147], v148 offset:1024
	ds_read_b128 v[156:159], v148 offset:2048
	ds_read_b128 v[160:163], v148 offset:3072
	v_add_u32_e32 v148, s52, v151
	ds_read_b128 v[164:167], v148
	ds_read_b128 v[168:171], v148 offset:1024
	ds_read_b128 v[172:175], v148 offset:2048
	ds_read_b128 v[176:179], v148 offset:3072
	s_add_u32 s30, s30, 0x80000
	s_addc_u32 s31, s31, 0
	s_mov_b32 m0, s44
	v_lshl_add_u64 v[220:221], s[30:31], 0, v[134:135]
	ds_read_b128 v[180:183], v155 offset:32768
	ds_read_b128 v[184:187], v155 offset:33792
	ds_read_b128 v[188:191], v155 offset:34816
	ds_read_b128 v[192:195], v155 offset:35840
	ds_read_b128 v[196:199], v155 offset:36864
	ds_read_b128 v[200:203], v155 offset:37888
	ds_read_b128 v[204:207], v155 offset:38912
	ds_read_b128 v[208:211], v155 offset:39936
	global_load_lds_dwordx4 v[220:221], off
	v_lshl_add_u64 v[220:221], s[30:31], 0, v[132:133]
	s_mov_b32 m0, s45
	s_nop 0
	global_load_lds_dwordx4 v[220:221], off
	s_waitcnt vmcnt(8)
	s_waitcnt lgkmcnt(0)
	s_barrier
	s_setprio 1
	s_waitcnt lgkmcnt(0)
	v_mfma_f32_16x16x32_bf16 v[126:129], v[140:143], v[180:183], v[126:129]
	v_mfma_f32_16x16x32_bf16 v[126:129], v[144:147], v[184:187], v[126:129]
	v_mfma_f32_16x16x32_bf16 v[122:125], v[160:163], v[184:187], v[122:125]
	v_mfma_f32_16x16x32_bf16 v[122:125], v[156:159], v[180:183], v[122:125]
	v_mfma_f32_16x16x32_bf16 v[106:109], v[156:159], v[188:191], v[106:109]
	v_mfma_f32_16x16x32_bf16 v[106:109], v[160:163], v[192:195], v[106:109]
	v_mfma_f32_16x16x32_bf16 v[110:113], v[144:147], v[192:195], v[110:113]
	v_mfma_f32_16x16x32_bf16 v[110:113], v[140:143], v[188:191], v[110:113]
	v_mfma_f32_16x16x32_bf16 v[94:97], v[140:143], v[196:199], v[94:97]
	v_mfma_f32_16x16x32_bf16 v[94:97], v[144:147], v[200:203], v[94:97]
	v_mfma_f32_16x16x32_bf16 v[90:93], v[160:163], v[200:203], v[90:93]
	v_mfma_f32_16x16x32_bf16 v[90:93], v[156:159], v[196:199], v[90:93]
	v_mfma_f32_16x16x32_bf16 v[74:77], v[156:159], v[204:207], v[74:77]
	v_mfma_f32_16x16x32_bf16 v[74:77], v[160:163], v[208:211], v[74:77]
	v_mfma_f32_16x16x32_bf16 v[78:81], v[144:147], v[208:211], v[78:81]
	v_mfma_f32_16x16x32_bf16 v[78:81], v[140:143], v[204:207], v[78:81]
	s_setprio 0
	s_setprio 1
	v_mfma_f32_16x16x32_bf16 v[118:121], v[164:167], v[180:183], v[118:121]
	v_mfma_f32_16x16x32_bf16 v[118:121], v[168:171], v[184:187], v[118:121]
	v_mfma_f32_16x16x32_bf16 v[114:117], v[176:179], v[184:187], v[114:117]
	v_mfma_f32_16x16x32_bf16 v[114:117], v[172:175], v[180:183], v[114:117]
	v_mfma_f32_16x16x32_bf16 v[98:101], v[172:175], v[188:191], v[98:101]
	v_mfma_f32_16x16x32_bf16 v[98:101], v[176:179], v[192:195], v[98:101]
	v_mfma_f32_16x16x32_bf16 v[102:105], v[168:171], v[192:195], v[102:105]
	v_mfma_f32_16x16x32_bf16 v[102:105], v[164:167], v[188:191], v[102:105]
	v_mfma_f32_16x16x32_bf16 v[86:89], v[164:167], v[196:199], v[86:89]
	v_mfma_f32_16x16x32_bf16 v[86:89], v[168:171], v[200:203], v[86:89]
	v_mfma_f32_16x16x32_bf16 v[82:85], v[176:179], v[200:203], v[82:85]
	v_mfma_f32_16x16x32_bf16 v[82:85], v[172:175], v[196:199], v[82:85]
	v_mfma_f32_16x16x32_bf16 v[66:69], v[172:175], v[204:207], v[66:69]
	v_mfma_f32_16x16x32_bf16 v[66:69], v[176:179], v[208:211], v[66:69]
	v_mfma_f32_16x16x32_bf16 v[70:73], v[168:171], v[208:211], v[70:73]
	v_mfma_f32_16x16x32_bf16 v[70:73], v[164:167], v[204:207], v[70:73]
	s_setprio 0
	s_barrier
; #define PG8_STAGE(bufoff, gbase, voff) do { _Pragma("unroll") for (int _i = 0; _i < 2; ++_i) \
;         __builtin_amdgcn_global_load_lds((const unsigned*)((const char*)(gbase) + (voff)[_i]), (LAS unsigned*)(lds + (bufoff) + ldsw + _i * 8192), 16, 0, 0); } while (0)
; #define PG8_LDA(dst, b, h) do { _Pragma("unroll") for (int m = 0; m < 4; ++m) _Pragma("unroll") for (int k = 0; k < 2; ++k) dst[m][k] = *(const LAS bf16x8*)(lds + PG8_SA(b, h) + aoff + m * 2048 + k * 1024); } while (0)
; #define PG8_MMA(ai, bj, At, Bt) do { __builtin_amdgcn_s_setprio(1); _Pragma("unroll") for (int m = 0; m < 4; ++m) _Pragma("unroll") for (int n = 0; n < 2; ++n) _Pragma("unroll") for (int k = 0; k < 2; ++k) \
;         acc[ai][bj][m][n] = __builtin_amdgcn_mfma_f32_16x16x32_bf16(Bt[n][k], At[m][k], acc[ai][bj][m][n], 0, 0, 0); __builtin_amdgcn_s_setprio(0); } while (0)
; #define PG8_WAIT_V(n) asm volatile("s_waitcnt vmcnt(" #n ")" ::: "memory")
; #define PG8_WAIT_L(n) asm volatile("s_waitcnt lgkmcnt(" #n ")" ::: "memory")
; #define PG8_BAR __builtin_amdgcn_s_barrier()
; #define PG8_SCHED __builtin_amdgcn_sched_barrier(0)
; template <class Epi, class Sched, bool ALIGN_EPI = false, bool SP2 = false>
; __device__ __forceinline__ void gemm_phase(LAS unsigned char* lds, const Gemm g, const Sched& S, const Epi& E) {
;     ...
;             PG8_LDA(At, 1, 1); PG8_STAGE(PG8_SB(1, 0), b3, voffB); PG8_STAGE(PG8_SB(1, 1), b3 + hstep, voffB); PG8_STAGE(PG8_SA(1, 0), a3, voffA);
;             PG8_WAIT_V(8); PG8_WAIT_L(0); PG8_BAR; PG8_MMA(1, 0, At, B0); PG8_MMA(1, 1, At, B1); PG8_BAR; PG8_SCHED;
;     ...
;         if constexpr (ALIGN_EPI) { if (wr == 0) PG8_BAR; }
	s_add_i32 s30, s51, s41
	v_lshl_add_u64 v[212:213], v[212:213], 0, s[12:13]
	s_mov_b32 m0, s30
	ds_read_b128 v[180:183], v155 offset:49152
	ds_read_b128 v[184:187], v155 offset:50176
	ds_read_b128 v[188:191], v155 offset:51200
	ds_read_b128 v[192:195], v155 offset:52224
	ds_read_b128 v[196:199], v155 offset:53248
	ds_read_b128 v[200:203], v155 offset:54272
	ds_read_b128 v[204:207], v155 offset:55296
	ds_read_b128 v[208:211], v155 offset:56320
	global_load_lds_dwordx4 v[212:213], off
	s_add_i32 m0, s30, 0x2000
	s_add_u32 s28, s28, 0x80080
	v_lshl_add_u64 v[212:213], v[214:215], 0, s[12:13]
	s_addc_u32 s29, s29, 0
	s_add_i32 s30, s52, s41
	global_load_lds_dwordx4 v[212:213], off
	v_lshl_add_u64 v[212:213], s[28:29], 0, v[0:1]
	s_mov_b32 m0, s30
	s_nop 0
	global_load_lds_dwordx4 v[212:213], off
	v_lshl_add_u64 v[212:213], s[28:29], 0, v[130:131]
	s_add_i32 m0, s30, 0x2000
	s_nop 0
	global_load_lds_dwordx4 v[212:213], off
	v_lshl_add_u64 v[212:213], v[216:217], 0, s[12:13]
	s_mov_b32 m0, s46
	s_nop 0
	global_load_lds_dwordx4 v[212:213], off
	v_lshl_add_u64 v[212:213], v[218:219], 0, s[12:13]
	s_mov_b32 m0, s47
	s_nop 0
	global_load_lds_dwordx4 v[212:213], off
	s_waitcnt vmcnt(8)
	s_waitcnt lgkmcnt(0)
	s_barrier
	s_setprio 1
	s_waitcnt lgkmcnt(0)
	v_mfma_f32_16x16x32_bf16 v[62:65], v[140:143], v[180:183], v[62:65]
	v_mfma_f32_16x16x32_bf16 v[62:65], v[144:147], v[184:187], v[62:65]
	v_mfma_f32_16x16x32_bf16 v[58:61], v[160:163], v[184:187], v[58:61]
	v_mfma_f32_16x16x32_bf16 v[58:61], v[156:159], v[180:183], v[58:61]
	v_mfma_f32_16x16x32_bf16 v[42:45], v[156:159], v[188:191], v[42:45]
	v_mfma_f32_16x16x32_bf16 v[42:45], v[160:163], v[192:195], v[42:45]
	v_mfma_f32_16x16x32_bf16 v[46:49], v[144:147], v[192:195], v[46:49]
	v_mfma_f32_16x16x32_bf16 v[46:49], v[140:143], v[188:191], v[46:49]
	v_mfma_f32_16x16x32_bf16 v[30:33], v[140:143], v[196:199], v[30:33]
	v_mfma_f32_16x16x32_bf16 v[30:33], v[144:147], v[200:203], v[30:33]
	v_mfma_f32_16x16x32_bf16 v[26:29], v[160:163], v[200:203], v[26:29]
	v_mfma_f32_16x16x32_bf16 v[26:29], v[156:159], v[196:199], v[26:29]
	v_mfma_f32_16x16x32_bf16 v[10:13], v[156:159], v[204:207], v[10:13]
	v_mfma_f32_16x16x32_bf16 v[10:13], v[160:163], v[208:211], v[10:13]
	v_mfma_f32_16x16x32_bf16 v[14:17], v[144:147], v[208:211], v[14:17]
	v_mfma_f32_16x16x32_bf16 v[14:17], v[140:143], v[204:207], v[14:17]
	s_setprio 0
	s_setprio 1
	v_mfma_f32_16x16x32_bf16 v[54:57], v[164:167], v[180:183], v[54:57]
	v_mfma_f32_16x16x32_bf16 v[54:57], v[168:171], v[184:187], v[54:57]
	v_mfma_f32_16x16x32_bf16 v[50:53], v[176:179], v[184:187], v[50:53]
	v_mfma_f32_16x16x32_bf16 v[50:53], v[172:175], v[180:183], v[50:53]
	v_mfma_f32_16x16x32_bf16 v[34:37], v[172:175], v[188:191], v[34:37]
	v_mfma_f32_16x16x32_bf16 v[34:37], v[176:179], v[192:195], v[34:37]
	v_mfma_f32_16x16x32_bf16 v[38:41], v[168:171], v[192:195], v[38:41]
	v_mfma_f32_16x16x32_bf16 v[38:41], v[164:167], v[188:191], v[38:41]
	v_mfma_f32_16x16x32_bf16 v[22:25], v[164:167], v[196:199], v[22:25]
	v_mfma_f32_16x16x32_bf16 v[22:25], v[168:171], v[200:203], v[22:25]
	v_mfma_f32_16x16x32_bf16 v[18:21], v[176:179], v[200:203], v[18:21]
	v_mfma_f32_16x16x32_bf16 v[18:21], v[172:175], v[196:199], v[18:21]
	v_mfma_f32_16x16x32_bf16 v[2:5], v[172:175], v[204:207], v[2:5]
	v_mfma_f32_16x16x32_bf16 v[2:5], v[176:179], v[208:211], v[2:5]
	v_mfma_f32_16x16x32_bf16 v[6:9], v[168:171], v[208:211], v[6:9]
	v_mfma_f32_16x16x32_bf16 v[6:9], v[164:167], v[204:207], v[6:9]
	s_setprio 0
	s_barrier
	s_add_i32 s50, s50, 2
	s_add_u32 s26, s26, 0x100
	s_addc_u32 s27, s27, 0
	s_add_u32 s35, s35, 0x100
	s_addc_u32 s49, s49, 0
	s_cmp_gt_u32 s50, 29
	s_cbranch_scc0 .LBB0_924
	s_and_b64 vcc, exec, s[16:17]
	s_cbranch_vccz .LBB0_927
	s_barrier

; #define PG8_STAGE(bufoff, gbase, voff) do { _Pragma("unroll") for (int _i = 0; _i < 2; ++_i) \
;         __builtin_amdgcn_global_load_lds((const unsigned*)((const char*)(gbase) + (voff)[_i]), (LAS unsigned*)(lds + (bufoff) + ldsw + _i * 8192), 16, 0, 0); } while (0)
; #define PG8_LDA(dst, b, h) do { _Pragma("unroll") for (int m = 0; m < 4; ++m) _Pragma("unroll") for (int k = 0; k < 2; ++k) dst[m][k] = *(const LAS bf16x8*)(lds + PG8_SA(b, h) + aoff + m * 2048 + k * 1024); } while (0)
; #define PG8_LDB(dst, b, h) do { _Pragma("unroll") for (int n = 0; n < 2; ++n) _Pragma("unroll") for (int k = 0; k < 2; ++k) dst[n][k] = *(const LAS bf16x8*)(lds + PG8_SB(b, h) + boff + n * 2048 + k * 1024); } while (0)
; #define PG8_MMA(ai, bj, At, Bt) do { __builtin_amdgcn_s_setprio(1); _Pragma("unroll") for (int m = 0; m < 4; ++m) _Pragma("unroll") for (int n = 0; n < 2; ++n) _Pragma("unroll") for (int k = 0; k < 2; ++k) \
;         acc[ai][bj][m][n] = __builtin_amdgcn_mfma_f32_16x16x32_bf16(Bt[n][k], At[m][k], acc[ai][bj][m][n], 0, 0, 0); __builtin_amdgcn_s_setprio(0); } while (0)
; #define PG8_WAIT_V(n) asm volatile("s_waitcnt vmcnt(" #n ")" ::: "memory")
; #define PG8_WAIT_L(n) asm volatile("s_waitcnt lgkmcnt(" #n ")" ::: "memory")
; #define PG8_BAR __builtin_amdgcn_s_barrier()
; template <class Epi, class Sched, bool ALIGN_EPI = false, bool SP2 = false>
; __device__ __forceinline__ void gemm_phase(LAS unsigned char* lds, const Gemm g, const Sched& S, const Epi& E) {
;     ...
;             const bool last = (t == nt - 2);
;             const char* a1 = cA + (size_t)(t + 1) * kstep;
;             const char* a2 = last ? nA : cA + (size_t)(t + 2) * kstep; const char* b2 = last ? nB : cB + (size_t)(t + 2) * kstep;
;             const char* a3 = a2 + kstep; const char* b3 = b2 + kstep;
;             if (last && has_next) S.a_ready(nxt);
;             if constexpr (SP2) {
;             PG8_LDB(B0, 0, 0); PG8_LDB(B1, 0, 1); PG8_SCHED; PG8_LDA(At, 0, 0); PG8_STAGE(PG8_SA(1, 1), a1 + hstep, voffA);
;             PG8_WAIT_V(8); PG8_WAIT_L(0); PG8_BAR; PG8_MMA(0, 0, At, B0); PG8_MMA(0, 1, At, B1); PG8_BAR; PG8_SCHED;
;             PG8_LDA(At, 0, 1); PG8_STAGE(PG8_SB(0, 0), b2, voffB); PG8_STAGE(PG8_SB(0, 1), b2 + hstep, voffB); PG8_STAGE(PG8_SA(0, 0), a2, voffA);
;             PG8_WAIT_V(8); PG8_WAIT_L(0); PG8_BAR; PG8_MMA(1, 0, At, B0); PG8_MMA(1, 1, At, B1); PG8_BAR; PG8_SCHED;
.LBB0_1007:
	s_add_u32 s24, s22, 0x100
	s_addc_u32 s25, s23, 0
	s_add_i32 s49, 0, 0x10000
	s_cmpk_eq_i32 s48, 0x54
	s_cselect_b32 s29, s1, s25
	s_cselect_b32 s28, s0, s24
	s_cselect_b32 s27, s21, s47
	s_cselect_b32 s26, s20, s46
	s_add_i32 s50, 0, 0x14000
	v_add_u32_e32 v126, s49, v247
	v_add_u32_e32 v158, s50, v247
	ds_read_b128 v[90:93], v126
	ds_read_b128 v[102:105], v126 offset:1024
	ds_read_b128 v[114:117], v126 offset:2048
	ds_read_b128 v[126:129], v126 offset:3072
	ds_read_b128 v[138:141], v158
	ds_read_b128 v[142:145], v158 offset:1024
	ds_read_b128 v[154:157], v158 offset:2048
	ds_read_b128 v[158:161], v158 offset:3072
	v_lshl_add_u64 v[204:205], s[22:23], 0, v[200:201]
	s_add_i32 m0, s8, 0xc000
	ds_read_b128 v[162:165], v249
	ds_read_b128 v[166:169], v249 offset:1024
	ds_read_b128 v[170:173], v249 offset:2048
	ds_read_b128 v[174:177], v249 offset:3072
	ds_read_b128 v[178:181], v249 offset:4096
	ds_read_b128 v[182:185], v249 offset:5120
	ds_read_b128 v[186:189], v249 offset:6144
	ds_read_b128 v[190:193], v249 offset:7168
	global_load_lds_dwordx4 v[204:205], off
	v_lshl_add_u64 v[204:205], s[22:23], 0, v[202:203]
	s_add_i32 m0, s8, 0xe000
	s_nop 0
	global_load_lds_dwordx4 v[204:205], off
	s_waitcnt vmcnt(8)
	s_waitcnt lgkmcnt(0)
	s_barrier
	s_setprio 1
	s_waitcnt lgkmcnt(0)
	v_mfma_f32_16x16x32_bf16 v[150:153], v[90:93], v[162:165], v[150:153]
	v_mfma_f32_16x16x32_bf16 v[150:153], v[102:105], v[166:169], v[150:153]
	v_mfma_f32_16x16x32_bf16 v[146:149], v[126:129], v[166:169], v[146:149]
	v_mfma_f32_16x16x32_bf16 v[146:149], v[114:117], v[162:165], v[146:149]
	v_mfma_f32_16x16x32_bf16 v[118:121], v[114:117], v[170:173], v[118:121]
	v_mfma_f32_16x16x32_bf16 v[118:121], v[126:129], v[174:177], v[118:121]
	v_mfma_f32_16x16x32_bf16 v[122:125], v[102:105], v[174:177], v[122:125]
	v_mfma_f32_16x16x32_bf16 v[122:125], v[90:93], v[170:173], v[122:125]
	v_mfma_f32_16x16x32_bf16 v[98:101], v[90:93], v[178:181], v[98:101]
	v_mfma_f32_16x16x32_bf16 v[98:101], v[102:105], v[182:185], v[98:101]
	v_mfma_f32_16x16x32_bf16 v[94:97], v[126:129], v[182:185], v[94:97]
	v_mfma_f32_16x16x32_bf16 v[94:97], v[114:117], v[178:181], v[94:97]
	v_mfma_f32_16x16x32_bf16 v[74:77], v[114:117], v[186:189], v[74:77]
	v_mfma_f32_16x16x32_bf16 v[74:77], v[126:129], v[190:193], v[74:77]
	v_mfma_f32_16x16x32_bf16 v[78:81], v[102:105], v[190:193], v[78:81]
	v_mfma_f32_16x16x32_bf16 v[78:81], v[90:93], v[186:189], v[78:81]
	s_setprio 0
	s_setprio 1
	v_mfma_f32_16x16x32_bf16 v[134:137], v[138:141], v[162:165], v[134:137]
	v_mfma_f32_16x16x32_bf16 v[134:137], v[142:145], v[166:169], v[134:137]
	v_mfma_f32_16x16x32_bf16 v[130:133], v[158:161], v[166:169], v[130:133]
	v_mfma_f32_16x16x32_bf16 v[130:133], v[154:157], v[162:165], v[130:133]
	v_mfma_f32_16x16x32_bf16 v[106:109], v[154:157], v[170:173], v[106:109]
	v_mfma_f32_16x16x32_bf16 v[106:109], v[158:161], v[174:177], v[106:109]
	v_mfma_f32_16x16x32_bf16 v[110:113], v[142:145], v[174:177], v[110:113]
	v_mfma_f32_16x16x32_bf16 v[110:113], v[138:141], v[170:173], v[110:113]
	v_mfma_f32_16x16x32_bf16 v[86:89], v[138:141], v[178:181], v[86:89]
	v_mfma_f32_16x16x32_bf16 v[86:89], v[142:145], v[182:185], v[86:89]
	v_mfma_f32_16x16x32_bf16 v[82:85], v[158:161], v[182:185], v[82:85]
	v_mfma_f32_16x16x32_bf16 v[82:85], v[154:157], v[178:181], v[82:85]
	v_mfma_f32_16x16x32_bf16 v[66:69], v[154:157], v[186:189], v[66:69]
	v_mfma_f32_16x16x32_bf16 v[66:69], v[158:161], v[190:193], v[66:69]
	v_mfma_f32_16x16x32_bf16 v[70:73], v[142:145], v[190:193], v[70:73]
	v_mfma_f32_16x16x32_bf16 v[70:73], v[138:141], v[186:189], v[70:73]
	s_setprio 0
	s_barrier
	s_add_i32 s22, s49, s7
	v_lshl_add_u64 v[204:205], s[26:27], 0, v[0:1]
	s_mov_b32 m0, s22
	ds_read_b128 v[162:165], v249 offset:16384
	ds_read_b128 v[166:169], v249 offset:17408
	ds_read_b128 v[170:173], v249 offset:18432
	ds_read_b128 v[174:177], v249 offset:19456
	ds_read_b128 v[178:181], v249 offset:20480
	ds_read_b128 v[182:185], v249 offset:21504
	ds_read_b128 v[186:189], v249 offset:22528
	ds_read_b128 v[190:193], v249 offset:23552
	global_load_lds_dwordx4 v[204:205], off
	s_add_i32 m0, s22, 0x2000
	s_add_u32 s22, s26, 0x160000
	v_lshl_add_u64 v[206:207], s[26:27], 0, v[194:195]
	s_addc_u32 s23, s27, 0
	s_add_i32 s49, s50, s7
	global_load_lds_dwordx4 v[206:207], off
	v_lshl_add_u64 v[208:209], s[22:23], 0, v[0:1]
	s_mov_b32 m0, s49
	v_lshl_add_u64 v[210:211], s[28:29], 0, v[196:197]
	global_load_lds_dwordx4 v[208:209], off
	v_lshl_add_u64 v[208:209], s[22:23], 0, v[194:195]
	s_add_i32 m0, s49, 0x2000
	s_nop 0
	global_load_lds_dwordx4 v[208:209], off
	v_lshl_add_u64 v[208:209], s[28:29], 0, v[198:199]
	s_mov_b32 m0, s8
	s_nop 0
	global_load_lds_dwordx4 v[208:209], off
	s_mov_b32 m0, s9
	s_nop 0
	global_load_lds_dwordx4 v[210:211], off
	s_waitcnt vmcnt(8)
	s_waitcnt lgkmcnt(0)
	s_barrier
; #define PG8_STAGE(bufoff, gbase, voff) do { _Pragma("unroll") for (int _i = 0; _i < 2; ++_i) \
;         __builtin_amdgcn_global_load_lds((const unsigned*)((const char*)(gbase) + (voff)[_i]), (LAS unsigned*)(lds + (bufoff) + ldsw + _i * 8192), 16, 0, 0); } while (0)
; #define PG8_LDA(dst, b, h) do { _Pragma("unroll") for (int m = 0; m < 4; ++m) _Pragma("unroll") for (int k = 0; k < 2; ++k) dst[m][k] = *(const LAS bf16x8*)(lds + PG8_SA(b, h) + aoff + m * 2048 + k * 1024); } while (0)
; #define PG8_LDB(dst, b, h) do { _Pragma("unroll") for (int n = 0; n < 2; ++n) _Pragma("unroll") for (int k = 0; k < 2; ++k) dst[n][k] = *(const LAS bf16x8*)(lds + PG8_SB(b, h) + boff + n * 2048 + k * 1024); } while (0)
; #define PG8_MMA(ai, bj, At, Bt) do { __builtin_amdgcn_s_setprio(1); _Pragma("unroll") for (int m = 0; m < 4; ++m) _Pragma("unroll") for (int n = 0; n < 2; ++n) _Pragma("unroll") for (int k = 0; k < 2; ++k) \
;         acc[ai][bj][m][n] = __builtin_amdgcn_mfma_f32_16x16x32_bf16(Bt[n][k], At[m][k], acc[ai][bj][m][n], 0, 0, 0); __builtin_amdgcn_s_setprio(0); } while (0)
; #define PG8_WAIT_V(n) asm volatile("s_waitcnt vmcnt(" #n ")" ::: "memory")
; #define PG8_WAIT_L(n) asm volatile("s_waitcnt lgkmcnt(" #n ")" ::: "memory")
; #define PG8_BAR __builtin_amdgcn_s_barrier()
; #define PG8_SCHED __builtin_amdgcn_sched_barrier(0)
; template <class Epi, class Sched, bool ALIGN_EPI = false, bool SP2 = false>
; __device__ __forceinline__ void gemm_phase(LAS unsigned char* lds, const Gemm g, const Sched& S, const Epi& E) {
;     ...
;             PG8_WAIT_V(8); PG8_WAIT_L(0); PG8_BAR; PG8_MMA(1, 0, At, B0); PG8_MMA(1, 1, At, B1); PG8_BAR; PG8_SCHED;
;             PG8_LDB(B0, 1, 0); PG8_LDB(B1, 1, 1); PG8_SCHED; PG8_LDA(At, 1, 0); PG8_STAGE(PG8_SA(0, 1), a2 + hstep, voffA);
;             PG8_WAIT_V(8); PG8_WAIT_L(0); PG8_BAR; PG8_MMA(0, 0, At, B0); PG8_MMA(0, 1, At, B1); PG8_BAR; PG8_SCHED;
	s_setprio 1
	s_waitcnt lgkmcnt(0)
	v_mfma_f32_16x16x32_bf16 v[62:65], v[90:93], v[162:165], v[62:65]
	v_mfma_f32_16x16x32_bf16 v[62:65], v[102:105], v[166:169], v[62:65]
	v_mfma_f32_16x16x32_bf16 v[58:61], v[126:129], v[166:169], v[58:61]
	v_mfma_f32_16x16x32_bf16 v[58:61], v[114:117], v[162:165], v[58:61]
	v_mfma_f32_16x16x32_bf16 v[42:45], v[114:117], v[170:173], v[42:45]
	v_mfma_f32_16x16x32_bf16 v[42:45], v[126:129], v[174:177], v[42:45]
	v_mfma_f32_16x16x32_bf16 v[46:49], v[102:105], v[174:177], v[46:49]
	v_mfma_f32_16x16x32_bf16 v[46:49], v[90:93], v[170:173], v[46:49]
	v_mfma_f32_16x16x32_bf16 v[30:33], v[90:93], v[178:181], v[30:33]
	v_mfma_f32_16x16x32_bf16 v[30:33], v[102:105], v[182:185], v[30:33]
	v_mfma_f32_16x16x32_bf16 v[26:29], v[126:129], v[182:185], v[26:29]
	v_mfma_f32_16x16x32_bf16 v[26:29], v[114:117], v[178:181], v[26:29]
	v_mfma_f32_16x16x32_bf16 v[10:13], v[114:117], v[186:189], v[10:13]
	v_mfma_f32_16x16x32_bf16 v[10:13], v[126:129], v[190:193], v[10:13]
	v_mfma_f32_16x16x32_bf16 v[14:17], v[102:105], v[190:193], v[14:17]
	v_mfma_f32_16x16x32_bf16 v[14:17], v[90:93], v[186:189], v[14:17]
	s_setprio 0
	s_setprio 1
	v_mfma_f32_16x16x32_bf16 v[54:57], v[138:141], v[162:165], v[54:57]
	v_mfma_f32_16x16x32_bf16 v[54:57], v[142:145], v[166:169], v[54:57]
	v_mfma_f32_16x16x32_bf16 v[50:53], v[158:161], v[166:169], v[50:53]
	v_mfma_f32_16x16x32_bf16 v[50:53], v[154:157], v[162:165], v[50:53]
	v_mfma_f32_16x16x32_bf16 v[34:37], v[154:157], v[170:173], v[34:37]
	v_mfma_f32_16x16x32_bf16 v[34:37], v[158:161], v[174:177], v[34:37]
	v_mfma_f32_16x16x32_bf16 v[38:41], v[142:145], v[174:177], v[38:41]
	v_mfma_f32_16x16x32_bf16 v[38:41], v[138:141], v[170:173], v[38:41]
	v_mfma_f32_16x16x32_bf16 v[22:25], v[138:141], v[178:181], v[22:25]
	v_mfma_f32_16x16x32_bf16 v[22:25], v[142:145], v[182:185], v[22:25]
	v_mfma_f32_16x16x32_bf16 v[18:21], v[158:161], v[182:185], v[18:21]
	v_mfma_f32_16x16x32_bf16 v[18:21], v[154:157], v[178:181], v[18:21]
	v_mfma_f32_16x16x32_bf16 v[2:5], v[154:157], v[186:189], v[2:5]
	v_mfma_f32_16x16x32_bf16 v[2:5], v[158:161], v[190:193], v[2:5]
	v_mfma_f32_16x16x32_bf16 v[6:9], v[142:145], v[190:193], v[6:9]
	v_mfma_f32_16x16x32_bf16 v[6:9], v[138:141], v[186:189], v[6:9]
	s_setprio 0
	s_barrier
	s_add_i32 s49, 0, 0x18000
	s_add_i32 s50, 0, 0x1c000
	v_add_u32_e32 v126, s49, v247
	v_add_u32_e32 v158, s50, v247
	ds_read_b128 v[90:93], v126
	ds_read_b128 v[102:105], v126 offset:1024
	ds_read_b128 v[114:117], v126 offset:2048
	ds_read_b128 v[126:129], v126 offset:3072
	ds_read_b128 v[138:141], v158
	ds_read_b128 v[142:145], v158 offset:1024
	ds_read_b128 v[154:157], v158 offset:2048
	ds_read_b128 v[158:161], v158 offset:3072
	s_add_u32 s22, s28, 0x160000
	s_addc_u32 s23, s29, 0
	s_mov_b32 m0, s30
	v_lshl_add_u64 v[212:213], s[22:23], 0, v[198:199]
	ds_read_b128 v[162:165], v249 offset:32768
	ds_read_b128 v[166:169], v249 offset:33792
	ds_read_b128 v[170:173], v249 offset:34816
	ds_read_b128 v[174:177], v249 offset:35840
	ds_read_b128 v[178:181], v249 offset:36864
	ds_read_b128 v[182:185], v249 offset:37888
	ds_read_b128 v[186:189], v249 offset:38912
	ds_read_b128 v[190:193], v249 offset:39936
	global_load_lds_dwordx4 v[212:213], off
	v_lshl_add_u64 v[212:213], s[22:23], 0, v[196:197]
	s_mov_b32 m0, s31
	s_nop 0
	global_load_lds_dwordx4 v[212:213], off
	s_waitcnt vmcnt(8)
	s_waitcnt lgkmcnt(0)
	s_barrier
	s_setprio 1
	s_waitcnt lgkmcnt(0)
	v_mfma_f32_16x16x32_bf16 v[150:153], v[90:93], v[162:165], v[150:153]
	v_mfma_f32_16x16x32_bf16 v[150:153], v[102:105], v[166:169], v[150:153]
	v_mfma_f32_16x16x32_bf16 v[146:149], v[126:129], v[166:169], v[146:149]
	v_mfma_f32_16x16x32_bf16 v[146:149], v[114:117], v[162:165], v[146:149]
	v_mfma_f32_16x16x32_bf16 v[118:121], v[114:117], v[170:173], v[118:121]
	v_mfma_f32_16x16x32_bf16 v[118:121], v[126:129], v[174:177], v[118:121]
	v_mfma_f32_16x16x32_bf16 v[122:125], v[102:105], v[174:177], v[122:125]
	v_mfma_f32_16x16x32_bf16 v[122:125], v[90:93], v[170:173], v[122:125]
	v_mfma_f32_16x16x32_bf16 v[98:101], v[90:93], v[178:181], v[98:101]
	v_mfma_f32_16x16x32_bf16 v[98:101], v[102:105], v[182:185], v[98:101]
	v_mfma_f32_16x16x32_bf16 v[94:97], v[126:129], v[182:185], v[94:97]
	v_mfma_f32_16x16x32_bf16 v[94:97], v[114:117], v[178:181], v[94:97]
	v_mfma_f32_16x16x32_bf16 v[74:77], v[114:117], v[186:189], v[74:77]
	v_mfma_f32_16x16x32_bf16 v[74:77], v[126:129], v[190:193], v[74:77]
	v_mfma_f32_16x16x32_bf16 v[78:81], v[102:105], v[190:193], v[78:81]
	v_mfma_f32_16x16x32_bf16 v[78:81], v[90:93], v[186:189], v[78:81]
	s_setprio 0
	s_setprio 1
	v_mfma_f32_16x16x32_bf16 v[134:137], v[138:141], v[162:165], v[134:137]
	v_mfma_f32_16x16x32_bf16 v[134:137], v[142:145], v[166:169], v[134:137]
	v_mfma_f32_16x16x32_bf16 v[130:133], v[158:161], v[166:169], v[130:133]
	v_mfma_f32_16x16x32_bf16 v[130:133], v[154:157], v[162:165], v[130:133]
	v_mfma_f32_16x16x32_bf16 v[106:109], v[154:157], v[170:173], v[106:109]
	v_mfma_f32_16x16x32_bf16 v[106:109], v[158:161], v[174:177], v[106:109]
	v_mfma_f32_16x16x32_bf16 v[110:113], v[142:145], v[174:177], v[110:113]
	v_mfma_f32_16x16x32_bf16 v[110:113], v[138:141], v[170:173], v[110:113]
	v_mfma_f32_16x16x32_bf16 v[86:89], v[138:141], v[178:181], v[86:89]
	v_mfma_f32_16x16x32_bf16 v[86:89], v[142:145], v[182:185], v[86:89]
	v_mfma_f32_16x16x32_bf16 v[82:85], v[158:161], v[182:185], v[82:85]
	v_mfma_f32_16x16x32_bf16 v[82:85], v[154:157], v[178:181], v[82:85]
	v_mfma_f32_16x16x32_bf16 v[66:69], v[154:157], v[186:189], v[66:69]
	v_mfma_f32_16x16x32_bf16 v[66:69], v[158:161], v[190:193], v[66:69]
	v_mfma_f32_16x16x32_bf16 v[70:73], v[142:145], v[190:193], v[70:73]
	v_mfma_f32_16x16x32_bf16 v[70:73], v[138:141], v[186:189], v[70:73]
	s_setprio 0
	s_barrier
; #define PG8_STAGE(bufoff, gbase, voff) do { _Pragma("unroll") for (int _i = 0; _i < 2; ++_i) \
;         __builtin_amdgcn_global_load_lds((const unsigned*)((const char*)(gbase) + (voff)[_i]), (LAS unsigned*)(lds + (bufoff) + ldsw + _i * 8192), 16, 0, 0); } while (0)
; #define PG8_LDA(dst, b, h) do { _Pragma("unroll") for (int m = 0; m < 4; ++m) _Pragma("unroll") for (int k = 0; k < 2; ++k) dst[m][k] = *(const LAS bf16x8*)(lds + PG8_SA(b, h) + aoff + m * 2048 + k * 1024); } while (0)
; #define PG8_MMA(ai, bj, At, Bt) do { __builtin_amdgcn_s_setprio(1); _Pragma("unroll") for (int m = 0; m < 4; ++m) _Pragma("unroll") for (int n = 0; n < 2; ++n) _Pragma("unroll") for (int k = 0; k < 2; ++k) \
;         acc[ai][bj][m][n] = __builtin_amdgcn_mfma_f32_16x16x32_bf16(Bt[n][k], At[m][k], acc[ai][bj][m][n], 0, 0, 0); __builtin_amdgcn_s_setprio(0); } while (0)
; #define PG8_WAIT_V(n) asm volatile("s_waitcnt vmcnt(" #n ")" ::: "memory")
; #define PG8_WAIT_L(n) asm volatile("s_waitcnt lgkmcnt(" #n ")" ::: "memory")
; #define PG8_BAR __builtin_amdgcn_s_barrier()
; #define PG8_SCHED __builtin_amdgcn_sched_barrier(0)
; template <class Epi, class Sched, bool ALIGN_EPI = false, bool SP2 = false>
; __device__ __forceinline__ void gemm_phase(LAS unsigned char* lds, const Gemm g, const Sched& S, const Epi& E) {
;     ...
;             PG8_LDA(At, 1, 1); PG8_STAGE(PG8_SB(1, 0), b3, voffB); PG8_STAGE(PG8_SB(1, 1), b3 + hstep, voffB); PG8_STAGE(PG8_SA(1, 0), a3, voffA);
;             PG8_WAIT_V(8); PG8_WAIT_L(0); PG8_BAR; PG8_MMA(1, 0, At, B0); PG8_MMA(1, 1, At, B1); PG8_BAR; PG8_SCHED;
;     ...
;         if constexpr (ALIGN_EPI) { if (wr == 0) PG8_BAR; }
	s_add_i32 s22, s49, s7
	v_lshl_add_u64 v[204:205], v[204:205], 0, s[12:13]
	s_mov_b32 m0, s22
	ds_read_b128 v[162:165], v249 offset:49152
	ds_read_b128 v[166:169], v249 offset:50176
	ds_read_b128 v[170:173], v249 offset:51200
	ds_read_b128 v[174:177], v249 offset:52224
	ds_read_b128 v[178:181], v249 offset:53248
	ds_read_b128 v[182:185], v249 offset:54272
	ds_read_b128 v[186:189], v249 offset:55296
	ds_read_b128 v[190:193], v249 offset:56320
	global_load_lds_dwordx4 v[204:205], off
	s_add_i32 m0, s22, 0x2000
	s_add_u32 s22, s26, 0x160080
	v_lshl_add_u64 v[204:205], v[206:207], 0, s[12:13]
	s_addc_u32 s23, s27, 0
	s_add_i32 s26, s50, s7
	global_load_lds_dwordx4 v[204:205], off
	v_lshl_add_u64 v[204:205], s[22:23], 0, v[0:1]
	s_mov_b32 m0, s26
	s_nop 0
	global_load_lds_dwordx4 v[204:205], off
	v_lshl_add_u64 v[204:205], s[22:23], 0, v[194:195]
	s_add_i32 m0, s26, 0x2000
	s_nop 0
	global_load_lds_dwordx4 v[204:205], off
	v_lshl_add_u64 v[204:205], v[208:209], 0, s[12:13]
	s_mov_b32 m0, s35
	s_nop 0
	global_load_lds_dwordx4 v[204:205], off
	v_lshl_add_u64 v[204:205], v[210:211], 0, s[12:13]
	s_mov_b32 m0, s40
	s_nop 0
	global_load_lds_dwordx4 v[204:205], off
	s_waitcnt vmcnt(8)
	s_waitcnt lgkmcnt(0)
	s_barrier
	s_setprio 1
	s_waitcnt lgkmcnt(0)
	v_mfma_f32_16x16x32_bf16 v[62:65], v[90:93], v[162:165], v[62:65]
	v_mfma_f32_16x16x32_bf16 v[62:65], v[102:105], v[166:169], v[62:65]
	v_mfma_f32_16x16x32_bf16 v[58:61], v[126:129], v[166:169], v[58:61]
	v_mfma_f32_16x16x32_bf16 v[58:61], v[114:117], v[162:165], v[58:61]
	v_mfma_f32_16x16x32_bf16 v[42:45], v[114:117], v[170:173], v[42:45]
	v_mfma_f32_16x16x32_bf16 v[42:45], v[126:129], v[174:177], v[42:45]
	v_mfma_f32_16x16x32_bf16 v[46:49], v[102:105], v[174:177], v[46:49]
	v_mfma_f32_16x16x32_bf16 v[46:49], v[90:93], v[170:173], v[46:49]
	v_mfma_f32_16x16x32_bf16 v[30:33], v[90:93], v[178:181], v[30:33]
	v_mfma_f32_16x16x32_bf16 v[30:33], v[102:105], v[182:185], v[30:33]
	v_mfma_f32_16x16x32_bf16 v[26:29], v[126:129], v[182:185], v[26:29]
	v_mfma_f32_16x16x32_bf16 v[26:29], v[114:117], v[178:181], v[26:29]
	v_mfma_f32_16x16x32_bf16 v[10:13], v[114:117], v[186:189], v[10:13]
	v_mfma_f32_16x16x32_bf16 v[10:13], v[126:129], v[190:193], v[10:13]
	v_mfma_f32_16x16x32_bf16 v[14:17], v[102:105], v[190:193], v[14:17]
	v_mfma_f32_16x16x32_bf16 v[14:17], v[90:93], v[186:189], v[14:17]
	s_setprio 0
	s_setprio 1
	v_mfma_f32_16x16x32_bf16 v[54:57], v[138:141], v[162:165], v[54:57]
	v_mfma_f32_16x16x32_bf16 v[54:57], v[142:145], v[166:169], v[54:57]
	v_mfma_f32_16x16x32_bf16 v[50:53], v[158:161], v[166:169], v[50:53]
	v_mfma_f32_16x16x32_bf16 v[50:53], v[154:157], v[162:165], v[50:53]
	v_mfma_f32_16x16x32_bf16 v[34:37], v[154:157], v[170:173], v[34:37]
	v_mfma_f32_16x16x32_bf16 v[34:37], v[158:161], v[174:177], v[34:37]
	v_mfma_f32_16x16x32_bf16 v[38:41], v[142:145], v[174:177], v[38:41]
	v_mfma_f32_16x16x32_bf16 v[38:41], v[138:141], v[170:173], v[38:41]
	v_mfma_f32_16x16x32_bf16 v[22:25], v[138:141], v[178:181], v[22:25]
	v_mfma_f32_16x16x32_bf16 v[22:25], v[142:145], v[182:185], v[22:25]
	v_mfma_f32_16x16x32_bf16 v[18:21], v[158:161], v[182:185], v[18:21]
	v_mfma_f32_16x16x32_bf16 v[18:21], v[154:157], v[178:181], v[18:21]
	v_mfma_f32_16x16x32_bf16 v[2:5], v[154:157], v[186:189], v[2:5]
	v_mfma_f32_16x16x32_bf16 v[2:5], v[158:161], v[190:193], v[2:5]
	v_mfma_f32_16x16x32_bf16 v[6:9], v[142:145], v[190:193], v[6:9]
	v_mfma_f32_16x16x32_bf16 v[6:9], v[138:141], v[186:189], v[6:9]
	s_setprio 0
	s_barrier
	s_add_i32 s48, s48, 2
	s_add_u32 s46, s46, 0x100
	s_addc_u32 s47, s47, 0
	s_cmpk_gt_u32 s48, 0x55
	s_mov_b64 s[22:23], s[24:25]
	s_cbranch_scc0 .LBB0_1007
	s_and_b64 vcc, exec, s[18:19]
	s_cbranch_vccz .LBB0_1010
	s_barrier
